# v74 + K-loop counter/pointer updates and exit test moved from behind the loop-back barrier into the last compute segment's MFMA shadow
# baseline (speedup 1.0000x reference)
.LBB0_184:
	s_add_i32 s90, s58, 2
	s_add_u32 s56, s54, 0x100
	s_addc_u32 s57, s55, 0
	s_add_i32 s91, 0, 0x10000
	s_cmp_eq_u32 s46, s58
	s_cselect_b32 s61, s18, s57
	s_cselect_b32 s60, s19, s56
	v_add_u32_e32 v140, s91, v143
	s_cselect_b32 s59, s22, s89
	s_cselect_b32 s58, s23, s47
	s_add_i32 vcc_lo, 0, 0x14000
	ds_read_b128 v[146:149], v140
	ds_read_b128 v[150:153], v140 offset:1024
	ds_read_b128 v[154:157], v140 offset:2048
	ds_read_b128 v[158:161], v140 offset:3072
	v_add_u32_e32 v140, vcc_lo, v143
	ds_read_b128 v[162:165], v140
	ds_read_b128 v[176:179], v140 offset:1024
	ds_read_b128 v[180:183], v140 offset:2048
	ds_read_b128 v[184:187], v140 offset:3072
	s_add_i32 m0, s39, 0xc000
	ds_read_b128 v[188:191], v144
	ds_read_b128 v[192:195], v144 offset:1024
	ds_read_b128 v[196:199], v144 offset:2048
	ds_read_b128 v[200:203], v144 offset:3072
	ds_read_b128 v[204:207], v144 offset:4096
	ds_read_b128 v[208:211], v144 offset:5120
	ds_read_b128 v[212:215], v144 offset:6144
	ds_read_b128 v[220:223], v144 offset:7168
	global_load_lds_dwordx4 v136, s[54:55]
	s_add_i32 m0, s39, 0xe000
	s_nop 0
	global_load_lds_dwordx4 v138, s[54:55]
	s_waitcnt vmcnt(8)
	s_waitcnt lgkmcnt(0)
	s_barrier
	v_mfma_f32_16x16x32_bf16 v[126:129], v[146:149], v[188:191], v[126:129]
	v_mfma_f32_16x16x32_bf16 v[122:125], v[154:157], v[188:191], v[122:125]
	v_mfma_f32_16x16x32_bf16 v[118:121], v[146:149], v[196:199], v[118:121]
	v_mfma_f32_16x16x32_bf16 v[110:113], v[154:157], v[196:199], v[110:113]
	v_mfma_f32_16x16x32_bf16 v[102:105], v[146:149], v[204:207], v[102:105]
	v_mfma_f32_16x16x32_bf16 v[94:97], v[154:157], v[204:207], v[94:97]
	v_mfma_f32_16x16x32_bf16 v[86:89], v[146:149], v[212:215], v[86:89]
	v_mfma_f32_16x16x32_bf16 v[78:81], v[154:157], v[212:215], v[78:81]
	v_mfma_f32_16x16x32_bf16 v[126:129], v[150:153], v[192:195], v[126:129]
	v_mfma_f32_16x16x32_bf16 v[122:125], v[158:161], v[192:195], v[122:125]
	v_mfma_f32_16x16x32_bf16 v[118:121], v[150:153], v[200:203], v[118:121]
	v_mfma_f32_16x16x32_bf16 v[110:113], v[158:161], v[200:203], v[110:113]
	v_mfma_f32_16x16x32_bf16 v[102:105], v[150:153], v[208:211], v[102:105]
	v_mfma_f32_16x16x32_bf16 v[94:97], v[158:161], v[208:211], v[94:97]
	v_mfma_f32_16x16x32_bf16 v[86:89], v[150:153], v[220:223], v[86:89]
	v_mfma_f32_16x16x32_bf16 v[78:81], v[158:161], v[220:223], v[78:81]
	v_mfma_f32_16x16x32_bf16 v[114:117], v[162:165], v[188:191], v[114:117]
	v_mfma_f32_16x16x32_bf16 v[106:109], v[180:183], v[188:191], v[106:109]
	v_mfma_f32_16x16x32_bf16 v[98:101], v[162:165], v[196:199], v[98:101]
	v_mfma_f32_16x16x32_bf16 v[90:93], v[180:183], v[196:199], v[90:93]
	v_mfma_f32_16x16x32_bf16 v[82:85], v[162:165], v[204:207], v[82:85]
	v_mfma_f32_16x16x32_bf16 v[74:77], v[180:183], v[204:207], v[74:77]
	v_mfma_f32_16x16x32_bf16 v[70:73], v[162:165], v[212:215], v[70:73]
	v_mfma_f32_16x16x32_bf16 v[66:69], v[180:183], v[212:215], v[66:69]
	v_mfma_f32_16x16x32_bf16 v[114:117], v[176:179], v[192:195], v[114:117]
	v_mfma_f32_16x16x32_bf16 v[106:109], v[184:187], v[192:195], v[106:109]
	v_mfma_f32_16x16x32_bf16 v[98:101], v[176:179], v[200:203], v[98:101]
	v_mfma_f32_16x16x32_bf16 v[90:93], v[184:187], v[200:203], v[90:93]
	v_mfma_f32_16x16x32_bf16 v[82:85], v[176:179], v[208:211], v[82:85]
	v_mfma_f32_16x16x32_bf16 v[74:77], v[184:187], v[208:211], v[74:77]
	v_mfma_f32_16x16x32_bf16 v[70:73], v[176:179], v[220:223], v[70:73]
	v_mfma_f32_16x16x32_bf16 v[66:69], v[184:187], v[220:223], v[66:69]
	s_barrier
	s_add_u32 s98, s58, s28
	s_addc_u32 s99, s59, s29
	s_add_u32 s100, s60, s28
	s_addc_u32 s101, s61, s29
	s_add_i32 s54, s91, s38
	s_mov_b32 m0, s54
	ds_read_b128 v[188:191], v144 offset:16384
	ds_read_b128 v[192:195], v144 offset:17408
	ds_read_b128 v[196:199], v144 offset:18432
	ds_read_b128 v[200:203], v144 offset:19456
	ds_read_b128 v[204:207], v144 offset:20480
	ds_read_b128 v[208:211], v144 offset:21504
	ds_read_b128 v[212:215], v144 offset:22528
	ds_read_b128 v[220:223], v144 offset:23552
	global_load_lds_dwordx4 v32, s[58:59]
	s_add_i32 m0, s54, 0x2000
	s_add_u32 s54, s58, 0xb0000
	s_addc_u32 s55, s59, 0
	s_add_i32 s91, vcc_lo, s38
	global_load_lds_dwordx4 v134, s[58:59]
	s_mov_b32 m0, s91
	s_nop 0
	global_load_lds_dwordx4 v32, s[54:55]
	s_add_i32 m0, s91, 0x2000
	s_nop 0
	global_load_lds_dwordx4 v134, s[54:55]
	s_mov_b32 m0, s39
	s_nop 0
	global_load_lds_dwordx4 v130, s[60:61]
	s_mov_b32 m0, s62
	s_nop 0
	global_load_lds_dwordx4 v132, s[60:61]
	s_waitcnt vmcnt(8)
	s_waitcnt lgkmcnt(0)
	s_barrier
	v_mfma_f32_16x16x32_bf16 v[62:65], v[146:149], v[188:191], v[62:65]
	v_mfma_f32_16x16x32_bf16 v[58:61], v[154:157], v[188:191], v[58:61]
	v_mfma_f32_16x16x32_bf16 v[54:57], v[146:149], v[196:199], v[54:57]
	v_mfma_f32_16x16x32_bf16 v[46:49], v[154:157], v[196:199], v[46:49]
	v_mfma_f32_16x16x32_bf16 v[38:41], v[146:149], v[204:207], v[38:41]
	v_mfma_f32_16x16x32_bf16 v[28:31], v[154:157], v[204:207], v[28:31]
	v_mfma_f32_16x16x32_bf16 v[20:23], v[146:149], v[212:215], v[20:23]
	v_mfma_f32_16x16x32_bf16 v[12:15], v[154:157], v[212:215], v[12:15]
	v_mfma_f32_16x16x32_bf16 v[62:65], v[150:153], v[192:195], v[62:65]
	v_mfma_f32_16x16x32_bf16 v[58:61], v[158:161], v[192:195], v[58:61]
	v_mfma_f32_16x16x32_bf16 v[54:57], v[150:153], v[200:203], v[54:57]
	v_mfma_f32_16x16x32_bf16 v[46:49], v[158:161], v[200:203], v[46:49]
	v_mfma_f32_16x16x32_bf16 v[38:41], v[150:153], v[208:211], v[38:41]
	v_mfma_f32_16x16x32_bf16 v[28:31], v[158:161], v[208:211], v[28:31]
	v_mfma_f32_16x16x32_bf16 v[20:23], v[150:153], v[220:223], v[20:23]
	v_mfma_f32_16x16x32_bf16 v[12:15], v[158:161], v[220:223], v[12:15]
	v_mfma_f32_16x16x32_bf16 v[50:53], v[162:165], v[188:191], v[50:53]
	v_mfma_f32_16x16x32_bf16 v[42:45], v[180:183], v[188:191], v[42:45]
	v_mfma_f32_16x16x32_bf16 v[34:37], v[162:165], v[196:199], v[34:37]
	v_mfma_f32_16x16x32_bf16 v[24:27], v[180:183], v[196:199], v[24:27]
	v_mfma_f32_16x16x32_bf16 v[16:19], v[162:165], v[204:207], v[16:19]
	v_mfma_f32_16x16x32_bf16 v[8:11], v[180:183], v[204:207], v[8:11]
	v_mfma_f32_16x16x32_bf16 v[4:7], v[162:165], v[212:215], v[4:7]
	v_mfma_f32_16x16x32_bf16 v[0:3], v[180:183], v[212:215], v[0:3]
	v_mfma_f32_16x16x32_bf16 v[50:53], v[176:179], v[192:195], v[50:53]
	v_mfma_f32_16x16x32_bf16 v[42:45], v[184:187], v[192:195], v[42:45]
	v_mfma_f32_16x16x32_bf16 v[34:37], v[176:179], v[200:203], v[34:37]
	v_mfma_f32_16x16x32_bf16 v[24:27], v[184:187], v[200:203], v[24:27]
	v_mfma_f32_16x16x32_bf16 v[16:19], v[176:179], v[208:211], v[16:19]
	v_mfma_f32_16x16x32_bf16 v[8:11], v[184:187], v[208:211], v[8:11]
	v_mfma_f32_16x16x32_bf16 v[4:7], v[176:179], v[220:223], v[4:7]
	v_mfma_f32_16x16x32_bf16 v[0:3], v[184:187], v[220:223], v[0:3]
	s_barrier
	s_add_i32 s91, 0, 0x18000
	v_add_u32_e32 v145, s91, v143
	s_add_i32 vcc_lo, 0, 0x1c000
	ds_read_b128 v[146:149], v145
	ds_read_b128 v[150:153], v145 offset:1024
	ds_read_b128 v[154:157], v145 offset:2048
	ds_read_b128 v[158:161], v145 offset:3072
	v_add_u32_e32 v145, vcc_lo, v143
	ds_read_b128 v[162:165], v145
	ds_read_b128 v[176:179], v145 offset:1024
	ds_read_b128 v[180:183], v145 offset:2048
	ds_read_b128 v[184:187], v145 offset:3072
	s_add_u32 s54, s60, 0xb0000
	s_addc_u32 s55, s61, 0
	s_mov_b32 m0, s63
	ds_read_b128 v[188:191], v144 offset:32768
	ds_read_b128 v[192:195], v144 offset:33792
	ds_read_b128 v[196:199], v144 offset:34816
	ds_read_b128 v[200:203], v144 offset:35840
	ds_read_b128 v[204:207], v144 offset:36864
	ds_read_b128 v[208:211], v144 offset:37888
	ds_read_b128 v[212:215], v144 offset:38912
	ds_read_b128 v[220:223], v144 offset:39936
	global_load_lds_dwordx4 v130, s[54:55]
	s_mov_b32 m0, s64
	s_nop 0
	global_load_lds_dwordx4 v132, s[54:55]
	s_waitcnt vmcnt(8)
	s_waitcnt lgkmcnt(0)
	s_barrier
	v_mfma_f32_16x16x32_bf16 v[126:129], v[146:149], v[188:191], v[126:129]
	v_mfma_f32_16x16x32_bf16 v[122:125], v[154:157], v[188:191], v[122:125]
	v_mfma_f32_16x16x32_bf16 v[118:121], v[146:149], v[196:199], v[118:121]
	v_mfma_f32_16x16x32_bf16 v[110:113], v[154:157], v[196:199], v[110:113]
	v_mfma_f32_16x16x32_bf16 v[102:105], v[146:149], v[204:207], v[102:105]
	v_mfma_f32_16x16x32_bf16 v[94:97], v[154:157], v[204:207], v[94:97]
	v_mfma_f32_16x16x32_bf16 v[86:89], v[146:149], v[212:215], v[86:89]
	v_mfma_f32_16x16x32_bf16 v[78:81], v[154:157], v[212:215], v[78:81]
	v_mfma_f32_16x16x32_bf16 v[126:129], v[150:153], v[192:195], v[126:129]
	v_mfma_f32_16x16x32_bf16 v[122:125], v[158:161], v[192:195], v[122:125]
	v_mfma_f32_16x16x32_bf16 v[118:121], v[150:153], v[200:203], v[118:121]
	v_mfma_f32_16x16x32_bf16 v[110:113], v[158:161], v[200:203], v[110:113]
	v_mfma_f32_16x16x32_bf16 v[102:105], v[150:153], v[208:211], v[102:105]
	v_mfma_f32_16x16x32_bf16 v[94:97], v[158:161], v[208:211], v[94:97]
	v_mfma_f32_16x16x32_bf16 v[86:89], v[150:153], v[220:223], v[86:89]
	v_mfma_f32_16x16x32_bf16 v[78:81], v[158:161], v[220:223], v[78:81]
	v_mfma_f32_16x16x32_bf16 v[114:117], v[162:165], v[188:191], v[114:117]
	v_mfma_f32_16x16x32_bf16 v[106:109], v[180:183], v[188:191], v[106:109]
	v_mfma_f32_16x16x32_bf16 v[98:101], v[162:165], v[196:199], v[98:101]
	v_mfma_f32_16x16x32_bf16 v[90:93], v[180:183], v[196:199], v[90:93]
	v_mfma_f32_16x16x32_bf16 v[82:85], v[162:165], v[204:207], v[82:85]
	v_mfma_f32_16x16x32_bf16 v[74:77], v[180:183], v[204:207], v[74:77]
	v_mfma_f32_16x16x32_bf16 v[70:73], v[162:165], v[212:215], v[70:73]
	v_mfma_f32_16x16x32_bf16 v[66:69], v[180:183], v[212:215], v[66:69]
	v_mfma_f32_16x16x32_bf16 v[114:117], v[176:179], v[192:195], v[114:117]
	v_mfma_f32_16x16x32_bf16 v[106:109], v[184:187], v[192:195], v[106:109]
	v_mfma_f32_16x16x32_bf16 v[98:101], v[176:179], v[200:203], v[98:101]
	v_mfma_f32_16x16x32_bf16 v[90:93], v[184:187], v[200:203], v[90:93]
	v_mfma_f32_16x16x32_bf16 v[82:85], v[176:179], v[208:211], v[82:85]
	v_mfma_f32_16x16x32_bf16 v[74:77], v[184:187], v[208:211], v[74:77]
	v_mfma_f32_16x16x32_bf16 v[70:73], v[176:179], v[220:223], v[70:73]
	v_mfma_f32_16x16x32_bf16 v[66:69], v[184:187], v[220:223], v[66:69]
	s_barrier
	s_add_i32 s54, s91, s38
	s_mov_b32 m0, s54
	ds_read_b128 v[188:191], v144 offset:49152
	ds_read_b128 v[192:195], v144 offset:50176
	ds_read_b128 v[196:199], v144 offset:51200
	ds_read_b128 v[200:203], v144 offset:52224
	ds_read_b128 v[204:207], v144 offset:53248
	ds_read_b128 v[208:211], v144 offset:54272
	ds_read_b128 v[212:215], v144 offset:55296
	ds_read_b128 v[220:223], v144 offset:56320
	global_load_lds_dwordx4 v32, s[98:99]
	s_add_i32 m0, s54, 0x2000
	s_add_u32 s54, s58, 0xb0080
	s_addc_u32 s55, s59, 0
	s_add_i32 s58, vcc_lo, s38
	global_load_lds_dwordx4 v134, s[98:99]
	s_mov_b32 m0, s58
	s_nop 0
	global_load_lds_dwordx4 v32, s[54:55]
	s_add_i32 m0, s58, 0x2000
	s_nop 0
	global_load_lds_dwordx4 v134, s[54:55]
	s_mov_b32 m0, s67
	s_nop 0
	global_load_lds_dwordx4 v130, s[100:101]
	s_mov_b32 m0, s77
	s_nop 0
	global_load_lds_dwordx4 v132, s[100:101]
	s_waitcnt vmcnt(8)
	s_waitcnt lgkmcnt(0)
	s_barrier
	v_mfma_f32_16x16x32_bf16 v[62:65], v[146:149], v[188:191], v[62:65]
	v_mfma_f32_16x16x32_bf16 v[58:61], v[154:157], v[188:191], v[58:61]
	s_add_u32 s47, s47, 0x100
	s_addc_u32 s89, s89, 0
	s_cmp_ge_i32 s90, s84
	s_mov_b64 s[54:55], s[56:57]
	s_mov_b32 s58, s90
	v_mfma_f32_16x16x32_bf16 v[54:57], v[146:149], v[196:199], v[54:57]
	v_mfma_f32_16x16x32_bf16 v[46:49], v[154:157], v[196:199], v[46:49]
	v_mfma_f32_16x16x32_bf16 v[38:41], v[146:149], v[204:207], v[38:41]
	v_mfma_f32_16x16x32_bf16 v[28:31], v[154:157], v[204:207], v[28:31]
	v_mfma_f32_16x16x32_bf16 v[20:23], v[146:149], v[212:215], v[20:23]
	v_mfma_f32_16x16x32_bf16 v[12:15], v[154:157], v[212:215], v[12:15]
	v_mfma_f32_16x16x32_bf16 v[62:65], v[150:153], v[192:195], v[62:65]
	v_mfma_f32_16x16x32_bf16 v[58:61], v[158:161], v[192:195], v[58:61]
	v_mfma_f32_16x16x32_bf16 v[54:57], v[150:153], v[200:203], v[54:57]
	v_mfma_f32_16x16x32_bf16 v[46:49], v[158:161], v[200:203], v[46:49]
	v_mfma_f32_16x16x32_bf16 v[38:41], v[150:153], v[208:211], v[38:41]
	v_mfma_f32_16x16x32_bf16 v[28:31], v[158:161], v[208:211], v[28:31]
	v_mfma_f32_16x16x32_bf16 v[20:23], v[150:153], v[220:223], v[20:23]
	v_mfma_f32_16x16x32_bf16 v[12:15], v[158:161], v[220:223], v[12:15]
	v_mfma_f32_16x16x32_bf16 v[50:53], v[162:165], v[188:191], v[50:53]
	v_mfma_f32_16x16x32_bf16 v[42:45], v[180:183], v[188:191], v[42:45]
	v_mfma_f32_16x16x32_bf16 v[34:37], v[162:165], v[196:199], v[34:37]
	v_mfma_f32_16x16x32_bf16 v[24:27], v[180:183], v[196:199], v[24:27]
	v_mfma_f32_16x16x32_bf16 v[16:19], v[162:165], v[204:207], v[16:19]
	v_mfma_f32_16x16x32_bf16 v[8:11], v[180:183], v[204:207], v[8:11]
	v_mfma_f32_16x16x32_bf16 v[4:7], v[162:165], v[212:215], v[4:7]
	v_mfma_f32_16x16x32_bf16 v[0:3], v[180:183], v[212:215], v[0:3]
	v_mfma_f32_16x16x32_bf16 v[50:53], v[176:179], v[192:195], v[50:53]
	v_mfma_f32_16x16x32_bf16 v[42:45], v[184:187], v[192:195], v[42:45]
	v_mfma_f32_16x16x32_bf16 v[34:37], v[176:179], v[200:203], v[34:37]
	v_mfma_f32_16x16x32_bf16 v[24:27], v[184:187], v[200:203], v[24:27]
	v_mfma_f32_16x16x32_bf16 v[16:19], v[176:179], v[208:211], v[16:19]
	v_mfma_f32_16x16x32_bf16 v[8:11], v[184:187], v[208:211], v[8:11]
	v_mfma_f32_16x16x32_bf16 v[4:7], v[176:179], v[220:223], v[4:7]
	v_mfma_f32_16x16x32_bf16 v[0:3], v[184:187], v[220:223], v[0:3]
	s_barrier
	s_cbranch_scc0 .LBB0_184
	s_and_b64 vcc, exec, s[26:27]
	s_cbranch_vccz .LBB0_187
	s_barrier

.LBB0_202:
	s_add_u32 s51, s62, 0xfffc0080
	s_addc_u32 s66, s63, -1
	s_add_i32 s79, 0, 0x10000
	s_cmp_eq_u32 s27, 12
	s_cselect_b32 vcc_hi, s59, s66
	s_cselect_b32 vcc_lo, s58, s51
	v_add_u32_e32 v140, s79, v143
	s_cselect_b32 s67, s61, s19
	s_cselect_b32 s66, s60, s18
	s_add_i32 s51, 0, 0x14000
	ds_read_b128 v[146:149], v140
	ds_read_b128 v[150:153], v140 offset:1024
	ds_read_b128 v[154:157], v140 offset:2048
	ds_read_b128 v[158:161], v140 offset:3072
	v_add_u32_e32 v140, s51, v143
	ds_read_b128 v[162:165], v140
	ds_read_b128 v[176:179], v140 offset:1024
	ds_read_b128 v[180:183], v140 offset:2048
	ds_read_b128 v[184:187], v140 offset:3072
	s_add_i32 m0, s33, 0xc000
	ds_read_b128 v[188:191], v144
	ds_read_b128 v[192:195], v144 offset:1024
	ds_read_b128 v[196:199], v144 offset:2048
	ds_read_b128 v[200:203], v144 offset:3072
	ds_read_b128 v[204:207], v144 offset:4096
	ds_read_b128 v[208:211], v144 offset:5120
	ds_read_b128 v[212:215], v144 offset:6144
	ds_read_b128 v[220:223], v144 offset:7168
	global_load_lds_dwordx4 v136, s[62:63]
	s_add_i32 m0, s33, 0xe000
	s_nop 0
	global_load_lds_dwordx4 v138, s[62:63]
	s_waitcnt vmcnt(8)
	s_waitcnt lgkmcnt(0)
	s_barrier
	v_mfma_f32_16x16x32_bf16 v[126:129], v[146:149], v[188:191], v[126:129]
	v_mfma_f32_16x16x32_bf16 v[118:121], v[154:157], v[188:191], v[118:121]
	v_mfma_f32_16x16x32_bf16 v[110:113], v[146:149], v[196:199], v[110:113]
	v_mfma_f32_16x16x32_bf16 v[102:105], v[154:157], v[196:199], v[102:105]
	v_mfma_f32_16x16x32_bf16 v[94:97], v[146:149], v[204:207], v[94:97]
	v_mfma_f32_16x16x32_bf16 v[86:89], v[154:157], v[204:207], v[86:89]
	v_mfma_f32_16x16x32_bf16 v[78:81], v[146:149], v[212:215], v[78:81]
	v_mfma_f32_16x16x32_bf16 v[70:73], v[154:157], v[212:215], v[70:73]
	v_mfma_f32_16x16x32_bf16 v[126:129], v[150:153], v[192:195], v[126:129]
	v_mfma_f32_16x16x32_bf16 v[118:121], v[158:161], v[192:195], v[118:121]
	v_mfma_f32_16x16x32_bf16 v[110:113], v[150:153], v[200:203], v[110:113]
	v_mfma_f32_16x16x32_bf16 v[102:105], v[158:161], v[200:203], v[102:105]
	v_mfma_f32_16x16x32_bf16 v[94:97], v[150:153], v[208:211], v[94:97]
	v_mfma_f32_16x16x32_bf16 v[86:89], v[158:161], v[208:211], v[86:89]
	v_mfma_f32_16x16x32_bf16 v[78:81], v[150:153], v[220:223], v[78:81]
	v_mfma_f32_16x16x32_bf16 v[70:73], v[158:161], v[220:223], v[70:73]
	v_mfma_f32_16x16x32_bf16 v[122:125], v[162:165], v[188:191], v[122:125]
	v_mfma_f32_16x16x32_bf16 v[114:117], v[180:183], v[188:191], v[114:117]
	v_mfma_f32_16x16x32_bf16 v[106:109], v[162:165], v[196:199], v[106:109]
	v_mfma_f32_16x16x32_bf16 v[98:101], v[180:183], v[196:199], v[98:101]
	v_mfma_f32_16x16x32_bf16 v[90:93], v[162:165], v[204:207], v[90:93]
	v_mfma_f32_16x16x32_bf16 v[82:85], v[180:183], v[204:207], v[82:85]
	v_mfma_f32_16x16x32_bf16 v[74:77], v[162:165], v[212:215], v[74:77]
	v_mfma_f32_16x16x32_bf16 v[66:69], v[180:183], v[212:215], v[66:69]
	v_mfma_f32_16x16x32_bf16 v[122:125], v[176:179], v[192:195], v[122:125]
	v_mfma_f32_16x16x32_bf16 v[114:117], v[184:187], v[192:195], v[114:117]
	v_mfma_f32_16x16x32_bf16 v[106:109], v[176:179], v[200:203], v[106:109]
	v_mfma_f32_16x16x32_bf16 v[98:101], v[184:187], v[200:203], v[98:101]
	v_mfma_f32_16x16x32_bf16 v[90:93], v[176:179], v[208:211], v[90:93]
	v_mfma_f32_16x16x32_bf16 v[82:85], v[184:187], v[208:211], v[82:85]
	v_mfma_f32_16x16x32_bf16 v[74:77], v[176:179], v[220:223], v[74:77]
	v_mfma_f32_16x16x32_bf16 v[66:69], v[184:187], v[220:223], v[66:69]
	s_barrier
	s_add_u32 s98, s66, s28
	s_addc_u32 s99, s67, s29
	s_add_u32 s100, vcc_lo, s28
	s_addc_u32 s101, vcc_hi, s29
	s_add_i32 s79, s79, s1
	s_mov_b32 m0, s79
	ds_read_b128 v[188:191], v144 offset:16384
	ds_read_b128 v[192:195], v144 offset:17408
	ds_read_b128 v[196:199], v144 offset:18432
	ds_read_b128 v[200:203], v144 offset:19456
	ds_read_b128 v[204:207], v144 offset:20480
	ds_read_b128 v[208:211], v144 offset:21504
	ds_read_b128 v[212:215], v144 offset:22528
	ds_read_b128 v[220:223], v144 offset:23552
	global_load_lds_dwordx4 v32, s[66:67]
	s_add_i32 m0, s79, 0x2000
	s_add_u32 s84, s66, 0x40000
	s_addc_u32 s85, s67, 0
	s_add_i32 s51, s51, s1
	global_load_lds_dwordx4 v130, s[66:67]
	s_mov_b32 m0, s51
	s_nop 0
	global_load_lds_dwordx4 v32, s[84:85]
	s_add_i32 m0, s51, 0x2000
	s_nop 0
	global_load_lds_dwordx4 v130, s[84:85]
	s_mov_b32 m0, s33
	s_nop 0
	global_load_lds_dwordx4 v134, vcc
	s_mov_b32 m0, s38
	s_nop 0
	global_load_lds_dwordx4 v132, vcc
	s_waitcnt vmcnt(8)
	s_waitcnt lgkmcnt(0)
	s_barrier
	v_mfma_f32_16x16x32_bf16 v[62:65], v[146:149], v[188:191], v[62:65]
	v_mfma_f32_16x16x32_bf16 v[54:57], v[154:157], v[188:191], v[54:57]
	v_mfma_f32_16x16x32_bf16 v[46:49], v[146:149], v[196:199], v[46:49]
	v_mfma_f32_16x16x32_bf16 v[38:41], v[154:157], v[196:199], v[38:41]
	v_mfma_f32_16x16x32_bf16 v[28:31], v[146:149], v[204:207], v[28:31]
	v_mfma_f32_16x16x32_bf16 v[20:23], v[154:157], v[204:207], v[20:23]
	v_mfma_f32_16x16x32_bf16 v[12:15], v[146:149], v[212:215], v[12:15]
	v_mfma_f32_16x16x32_bf16 v[4:7], v[154:157], v[212:215], v[4:7]
	v_mfma_f32_16x16x32_bf16 v[62:65], v[150:153], v[192:195], v[62:65]
	v_mfma_f32_16x16x32_bf16 v[54:57], v[158:161], v[192:195], v[54:57]
	v_mfma_f32_16x16x32_bf16 v[46:49], v[150:153], v[200:203], v[46:49]
	v_mfma_f32_16x16x32_bf16 v[38:41], v[158:161], v[200:203], v[38:41]
	v_mfma_f32_16x16x32_bf16 v[28:31], v[150:153], v[208:211], v[28:31]
	v_mfma_f32_16x16x32_bf16 v[20:23], v[158:161], v[208:211], v[20:23]
	v_mfma_f32_16x16x32_bf16 v[12:15], v[150:153], v[220:223], v[12:15]
	v_mfma_f32_16x16x32_bf16 v[4:7], v[158:161], v[220:223], v[4:7]
	v_mfma_f32_16x16x32_bf16 v[58:61], v[162:165], v[188:191], v[58:61]
	v_mfma_f32_16x16x32_bf16 v[50:53], v[180:183], v[188:191], v[50:53]
	v_mfma_f32_16x16x32_bf16 v[42:45], v[162:165], v[196:199], v[42:45]
	v_mfma_f32_16x16x32_bf16 v[34:37], v[180:183], v[196:199], v[34:37]
	v_mfma_f32_16x16x32_bf16 v[24:27], v[162:165], v[204:207], v[24:27]
	v_mfma_f32_16x16x32_bf16 v[16:19], v[180:183], v[204:207], v[16:19]
	v_mfma_f32_16x16x32_bf16 v[8:11], v[162:165], v[212:215], v[8:11]
	v_mfma_f32_16x16x32_bf16 v[0:3], v[180:183], v[212:215], v[0:3]
	v_mfma_f32_16x16x32_bf16 v[58:61], v[176:179], v[192:195], v[58:61]
	v_mfma_f32_16x16x32_bf16 v[50:53], v[184:187], v[192:195], v[50:53]
	v_mfma_f32_16x16x32_bf16 v[42:45], v[176:179], v[200:203], v[42:45]
	v_mfma_f32_16x16x32_bf16 v[34:37], v[184:187], v[200:203], v[34:37]
	v_mfma_f32_16x16x32_bf16 v[24:27], v[176:179], v[208:211], v[24:27]
	v_mfma_f32_16x16x32_bf16 v[16:19], v[184:187], v[208:211], v[16:19]
	v_mfma_f32_16x16x32_bf16 v[8:11], v[176:179], v[220:223], v[8:11]
	v_mfma_f32_16x16x32_bf16 v[0:3], v[184:187], v[220:223], v[0:3]
	s_barrier
	s_add_i32 s51, 0, 0x18000
	v_add_u32_e32 v145, s51, v143
	s_add_i32 s79, 0, 0x1c000
	ds_read_b128 v[146:149], v145
	ds_read_b128 v[150:153], v145 offset:1024
	ds_read_b128 v[154:157], v145 offset:2048
	ds_read_b128 v[158:161], v145 offset:3072
	v_add_u32_e32 v145, s79, v143
	ds_read_b128 v[162:165], v145
	ds_read_b128 v[176:179], v145 offset:1024
	ds_read_b128 v[180:183], v145 offset:2048
	ds_read_b128 v[184:187], v145 offset:3072
	s_add_u32 s84, vcc_lo, 0x40000
	s_addc_u32 s85, vcc_hi, 0
	s_mov_b32 m0, s39
	ds_read_b128 v[188:191], v144 offset:32768
	ds_read_b128 v[192:195], v144 offset:33792
	ds_read_b128 v[196:199], v144 offset:34816
	ds_read_b128 v[200:203], v144 offset:35840
	ds_read_b128 v[204:207], v144 offset:36864
	ds_read_b128 v[208:211], v144 offset:37888
	ds_read_b128 v[212:215], v144 offset:38912
	ds_read_b128 v[220:223], v144 offset:39936
	global_load_lds_dwordx4 v134, s[84:85]
	s_mov_b32 m0, s46
	s_nop 0
	global_load_lds_dwordx4 v132, s[84:85]
	s_waitcnt vmcnt(8)
	s_waitcnt lgkmcnt(0)
	s_barrier
	v_mfma_f32_16x16x32_bf16 v[126:129], v[146:149], v[188:191], v[126:129]
	v_mfma_f32_16x16x32_bf16 v[118:121], v[154:157], v[188:191], v[118:121]
	v_mfma_f32_16x16x32_bf16 v[110:113], v[146:149], v[196:199], v[110:113]
	v_mfma_f32_16x16x32_bf16 v[102:105], v[154:157], v[196:199], v[102:105]
	v_mfma_f32_16x16x32_bf16 v[94:97], v[146:149], v[204:207], v[94:97]
	v_mfma_f32_16x16x32_bf16 v[86:89], v[154:157], v[204:207], v[86:89]
	v_mfma_f32_16x16x32_bf16 v[78:81], v[146:149], v[212:215], v[78:81]
	v_mfma_f32_16x16x32_bf16 v[70:73], v[154:157], v[212:215], v[70:73]
	v_mfma_f32_16x16x32_bf16 v[126:129], v[150:153], v[192:195], v[126:129]
	v_mfma_f32_16x16x32_bf16 v[118:121], v[158:161], v[192:195], v[118:121]
	v_mfma_f32_16x16x32_bf16 v[110:113], v[150:153], v[200:203], v[110:113]
	v_mfma_f32_16x16x32_bf16 v[102:105], v[158:161], v[200:203], v[102:105]
	v_mfma_f32_16x16x32_bf16 v[94:97], v[150:153], v[208:211], v[94:97]
	v_mfma_f32_16x16x32_bf16 v[86:89], v[158:161], v[208:211], v[86:89]
	v_mfma_f32_16x16x32_bf16 v[78:81], v[150:153], v[220:223], v[78:81]
	v_mfma_f32_16x16x32_bf16 v[70:73], v[158:161], v[220:223], v[70:73]
	v_mfma_f32_16x16x32_bf16 v[122:125], v[162:165], v[188:191], v[122:125]
	v_mfma_f32_16x16x32_bf16 v[114:117], v[180:183], v[188:191], v[114:117]
	v_mfma_f32_16x16x32_bf16 v[106:109], v[162:165], v[196:199], v[106:109]
	v_mfma_f32_16x16x32_bf16 v[98:101], v[180:183], v[196:199], v[98:101]
	v_mfma_f32_16x16x32_bf16 v[90:93], v[162:165], v[204:207], v[90:93]
	v_mfma_f32_16x16x32_bf16 v[82:85], v[180:183], v[204:207], v[82:85]
	v_mfma_f32_16x16x32_bf16 v[74:77], v[162:165], v[212:215], v[74:77]
	v_mfma_f32_16x16x32_bf16 v[66:69], v[180:183], v[212:215], v[66:69]
	v_mfma_f32_16x16x32_bf16 v[122:125], v[176:179], v[192:195], v[122:125]
	v_mfma_f32_16x16x32_bf16 v[114:117], v[184:187], v[192:195], v[114:117]
	v_mfma_f32_16x16x32_bf16 v[106:109], v[176:179], v[200:203], v[106:109]
	v_mfma_f32_16x16x32_bf16 v[98:101], v[184:187], v[200:203], v[98:101]
	v_mfma_f32_16x16x32_bf16 v[90:93], v[176:179], v[208:211], v[90:93]
	v_mfma_f32_16x16x32_bf16 v[82:85], v[184:187], v[208:211], v[82:85]
	v_mfma_f32_16x16x32_bf16 v[74:77], v[176:179], v[220:223], v[74:77]
	v_mfma_f32_16x16x32_bf16 v[66:69], v[184:187], v[220:223], v[66:69]
	s_barrier
	s_add_i32 s51, s51, s1
	s_mov_b32 m0, s51
	ds_read_b128 v[188:191], v144 offset:49152
	ds_read_b128 v[192:195], v144 offset:50176
	ds_read_b128 v[196:199], v144 offset:51200
	ds_read_b128 v[200:203], v144 offset:52224
	ds_read_b128 v[204:207], v144 offset:53248
	ds_read_b128 v[208:211], v144 offset:54272
	ds_read_b128 v[212:215], v144 offset:55296
	ds_read_b128 v[220:223], v144 offset:56320
	global_load_lds_dwordx4 v32, s[98:99]
	s_add_i32 m0, s51, 0x2000
	s_add_u32 s66, s66, 0x40080
	s_addc_u32 s67, s67, 0
	s_add_i32 s51, s79, s1
	global_load_lds_dwordx4 v130, s[98:99]
	s_mov_b32 m0, s51
	s_nop 0
	global_load_lds_dwordx4 v32, s[66:67]
	s_add_i32 m0, s51, 0x2000
	s_nop 0
	global_load_lds_dwordx4 v130, s[66:67]
	s_mov_b32 m0, s64
	s_nop 0
	global_load_lds_dwordx4 v134, s[100:101]
	s_mov_b32 m0, s65
	s_nop 0
	global_load_lds_dwordx4 v132, s[100:101]
	s_waitcnt vmcnt(8)
	s_waitcnt lgkmcnt(0)
	s_barrier
	v_mfma_f32_16x16x32_bf16 v[62:65], v[146:149], v[188:191], v[62:65]
	v_mfma_f32_16x16x32_bf16 v[54:57], v[154:157], v[188:191], v[54:57]
	s_add_i32 s27, s27, 2
	s_add_u32 s62, s62, 0x100
	s_addc_u32 s63, s63, 0
	s_add_u32 s18, s18, 0x100
	s_addc_u32 s19, s19, 0
	s_cmp_gt_u32 s27, 13
	v_mfma_f32_16x16x32_bf16 v[46:49], v[146:149], v[196:199], v[46:49]
	v_mfma_f32_16x16x32_bf16 v[38:41], v[154:157], v[196:199], v[38:41]
	v_mfma_f32_16x16x32_bf16 v[28:31], v[146:149], v[204:207], v[28:31]
	v_mfma_f32_16x16x32_bf16 v[20:23], v[154:157], v[204:207], v[20:23]
	v_mfma_f32_16x16x32_bf16 v[12:15], v[146:149], v[212:215], v[12:15]
	v_mfma_f32_16x16x32_bf16 v[4:7], v[154:157], v[212:215], v[4:7]
	v_mfma_f32_16x16x32_bf16 v[62:65], v[150:153], v[192:195], v[62:65]
	v_mfma_f32_16x16x32_bf16 v[54:57], v[158:161], v[192:195], v[54:57]
	v_mfma_f32_16x16x32_bf16 v[46:49], v[150:153], v[200:203], v[46:49]
	v_mfma_f32_16x16x32_bf16 v[38:41], v[158:161], v[200:203], v[38:41]
	v_mfma_f32_16x16x32_bf16 v[28:31], v[150:153], v[208:211], v[28:31]
	v_mfma_f32_16x16x32_bf16 v[20:23], v[158:161], v[208:211], v[20:23]
	v_mfma_f32_16x16x32_bf16 v[12:15], v[150:153], v[220:223], v[12:15]
	v_mfma_f32_16x16x32_bf16 v[4:7], v[158:161], v[220:223], v[4:7]
	v_mfma_f32_16x16x32_bf16 v[58:61], v[162:165], v[188:191], v[58:61]
	v_mfma_f32_16x16x32_bf16 v[50:53], v[180:183], v[188:191], v[50:53]
	v_mfma_f32_16x16x32_bf16 v[42:45], v[162:165], v[196:199], v[42:45]
	v_mfma_f32_16x16x32_bf16 v[34:37], v[180:183], v[196:199], v[34:37]
	v_mfma_f32_16x16x32_bf16 v[24:27], v[162:165], v[204:207], v[24:27]
	v_mfma_f32_16x16x32_bf16 v[16:19], v[180:183], v[204:207], v[16:19]
	v_mfma_f32_16x16x32_bf16 v[8:11], v[162:165], v[212:215], v[8:11]
	v_mfma_f32_16x16x32_bf16 v[0:3], v[180:183], v[212:215], v[0:3]
	v_mfma_f32_16x16x32_bf16 v[58:61], v[176:179], v[192:195], v[58:61]
	v_mfma_f32_16x16x32_bf16 v[50:53], v[184:187], v[192:195], v[50:53]
	v_mfma_f32_16x16x32_bf16 v[42:45], v[176:179], v[200:203], v[42:45]
	v_mfma_f32_16x16x32_bf16 v[34:37], v[184:187], v[200:203], v[34:37]
	v_mfma_f32_16x16x32_bf16 v[24:27], v[176:179], v[208:211], v[24:27]
	v_mfma_f32_16x16x32_bf16 v[16:19], v[184:187], v[208:211], v[16:19]
	v_mfma_f32_16x16x32_bf16 v[8:11], v[176:179], v[220:223], v[8:11]
	v_mfma_f32_16x16x32_bf16 v[0:3], v[184:187], v[220:223], v[0:3]
	s_barrier
	s_cbranch_scc0 .LBB0_202
	s_and_b64 vcc, exec, s[24:25]
	s_cbranch_vccz .LBB0_205
	s_barrier

.LBB0_333:
	s_add_i32 s66, s52, 2
	s_add_u32 s53, s50, 0xfffc0080
	s_addc_u32 s54, s51, -1
	s_add_i32 s67, 0, 0x10000
	s_cmp_eq_u32 s27, s52
	s_cselect_b32 s55, s18, s54
	s_cselect_b32 s54, s19, s53
	v_add_u32_e32 v140, s67, v143
	s_cselect_b32 s53, s22, s65
	s_cselect_b32 s52, s23, s64
	s_add_i32 s69, 0, 0x14000
	ds_read_b128 v[146:149], v140
	ds_read_b128 v[150:153], v140 offset:1024
	ds_read_b128 v[154:157], v140 offset:2048
	ds_read_b128 v[158:161], v140 offset:3072
	v_add_u32_e32 v140, s69, v143
	ds_read_b128 v[162:165], v140
	ds_read_b128 v[176:179], v140 offset:1024
	ds_read_b128 v[180:183], v140 offset:2048
	ds_read_b128 v[184:187], v140 offset:3072
	s_add_i32 m0, s33, 0xc000
	ds_read_b128 v[188:191], v144
	ds_read_b128 v[192:195], v144 offset:1024
	ds_read_b128 v[196:199], v144 offset:2048
	ds_read_b128 v[200:203], v144 offset:3072
	ds_read_b128 v[204:207], v144 offset:4096
	ds_read_b128 v[208:211], v144 offset:5120
	ds_read_b128 v[212:215], v144 offset:6144
	ds_read_b128 v[220:223], v144 offset:7168
	global_load_lds_dwordx4 v136, s[50:51]
	s_add_i32 m0, s33, 0xe000
	s_nop 0
	global_load_lds_dwordx4 v138, s[50:51]
	s_waitcnt vmcnt(8)
	s_waitcnt lgkmcnt(0)
	s_barrier
	v_mfma_f32_16x16x32_bf16 v[126:129], v[146:149], v[188:191], v[126:129]
	v_mfma_f32_16x16x32_bf16 v[122:125], v[154:157], v[188:191], v[122:125]
	v_mfma_f32_16x16x32_bf16 v[118:121], v[146:149], v[196:199], v[118:121]
	v_mfma_f32_16x16x32_bf16 v[110:113], v[154:157], v[196:199], v[110:113]
	v_mfma_f32_16x16x32_bf16 v[102:105], v[146:149], v[204:207], v[102:105]
	v_mfma_f32_16x16x32_bf16 v[94:97], v[154:157], v[204:207], v[94:97]
	v_mfma_f32_16x16x32_bf16 v[86:89], v[146:149], v[212:215], v[86:89]
	v_mfma_f32_16x16x32_bf16 v[78:81], v[154:157], v[212:215], v[78:81]
	v_mfma_f32_16x16x32_bf16 v[126:129], v[150:153], v[192:195], v[126:129]
	v_mfma_f32_16x16x32_bf16 v[122:125], v[158:161], v[192:195], v[122:125]
	v_mfma_f32_16x16x32_bf16 v[118:121], v[150:153], v[200:203], v[118:121]
	v_mfma_f32_16x16x32_bf16 v[110:113], v[158:161], v[200:203], v[110:113]
	v_mfma_f32_16x16x32_bf16 v[102:105], v[150:153], v[208:211], v[102:105]
	v_mfma_f32_16x16x32_bf16 v[94:97], v[158:161], v[208:211], v[94:97]
	v_mfma_f32_16x16x32_bf16 v[86:89], v[150:153], v[220:223], v[86:89]
	v_mfma_f32_16x16x32_bf16 v[78:81], v[158:161], v[220:223], v[78:81]
	v_mfma_f32_16x16x32_bf16 v[114:117], v[162:165], v[188:191], v[114:117]
	v_mfma_f32_16x16x32_bf16 v[106:109], v[180:183], v[188:191], v[106:109]
	v_mfma_f32_16x16x32_bf16 v[98:101], v[162:165], v[196:199], v[98:101]
	v_mfma_f32_16x16x32_bf16 v[90:93], v[180:183], v[196:199], v[90:93]
	v_mfma_f32_16x16x32_bf16 v[82:85], v[162:165], v[204:207], v[82:85]
	v_mfma_f32_16x16x32_bf16 v[74:77], v[180:183], v[204:207], v[74:77]
	v_mfma_f32_16x16x32_bf16 v[70:73], v[162:165], v[212:215], v[70:73]
	v_mfma_f32_16x16x32_bf16 v[66:69], v[180:183], v[212:215], v[66:69]
	v_mfma_f32_16x16x32_bf16 v[114:117], v[176:179], v[192:195], v[114:117]
	v_mfma_f32_16x16x32_bf16 v[106:109], v[184:187], v[192:195], v[106:109]
	v_mfma_f32_16x16x32_bf16 v[98:101], v[176:179], v[200:203], v[98:101]
	v_mfma_f32_16x16x32_bf16 v[90:93], v[184:187], v[200:203], v[90:93]
	v_mfma_f32_16x16x32_bf16 v[82:85], v[176:179], v[208:211], v[82:85]
	v_mfma_f32_16x16x32_bf16 v[74:77], v[184:187], v[208:211], v[74:77]
	v_mfma_f32_16x16x32_bf16 v[70:73], v[176:179], v[220:223], v[70:73]
	v_mfma_f32_16x16x32_bf16 v[66:69], v[184:187], v[220:223], v[66:69]
	s_barrier
	s_add_u32 s98, s52, s28
	s_addc_u32 s99, s53, s29
	s_add_u32 s100, s54, s28
	s_addc_u32 s101, s55, s29
	s_add_i32 s67, s67, s13
	s_mov_b32 m0, s67
	ds_read_b128 v[188:191], v144 offset:16384
	ds_read_b128 v[192:195], v144 offset:17408
	ds_read_b128 v[196:199], v144 offset:18432
	ds_read_b128 v[200:203], v144 offset:19456
	ds_read_b128 v[204:207], v144 offset:20480
	ds_read_b128 v[208:211], v144 offset:21504
	ds_read_b128 v[212:215], v144 offset:22528
	ds_read_b128 v[220:223], v144 offset:23552
	global_load_lds_dwordx4 v32, s[52:53]
	s_add_i32 m0, s67, 0x2000
	s_add_u32 s78, s52, 0x40000
	s_addc_u32 s79, s53, 0
	s_add_i32 s67, s69, s13
	global_load_lds_dwordx4 v134, s[52:53]
	s_mov_b32 m0, s67
	s_nop 0
	global_load_lds_dwordx4 v32, s[78:79]
	s_add_i32 m0, s67, 0x2000
	s_nop 0
	global_load_lds_dwordx4 v134, s[78:79]
	s_mov_b32 m0, s33
	s_nop 0
	global_load_lds_dwordx4 v130, s[54:55]
	s_mov_b32 m0, s38
	s_nop 0
	global_load_lds_dwordx4 v132, s[54:55]
	s_waitcnt vmcnt(8)
	s_waitcnt lgkmcnt(0)
	s_barrier
	v_mfma_f32_16x16x32_bf16 v[62:65], v[146:149], v[188:191], v[62:65]
	v_mfma_f32_16x16x32_bf16 v[58:61], v[154:157], v[188:191], v[58:61]
	v_mfma_f32_16x16x32_bf16 v[54:57], v[146:149], v[196:199], v[54:57]
	v_mfma_f32_16x16x32_bf16 v[46:49], v[154:157], v[196:199], v[46:49]
	v_mfma_f32_16x16x32_bf16 v[38:41], v[146:149], v[204:207], v[38:41]
	v_mfma_f32_16x16x32_bf16 v[28:31], v[154:157], v[204:207], v[28:31]
	v_mfma_f32_16x16x32_bf16 v[20:23], v[146:149], v[212:215], v[20:23]
	v_mfma_f32_16x16x32_bf16 v[12:15], v[154:157], v[212:215], v[12:15]
	v_mfma_f32_16x16x32_bf16 v[62:65], v[150:153], v[192:195], v[62:65]
	v_mfma_f32_16x16x32_bf16 v[58:61], v[158:161], v[192:195], v[58:61]
	v_mfma_f32_16x16x32_bf16 v[54:57], v[150:153], v[200:203], v[54:57]
	v_mfma_f32_16x16x32_bf16 v[46:49], v[158:161], v[200:203], v[46:49]
	v_mfma_f32_16x16x32_bf16 v[38:41], v[150:153], v[208:211], v[38:41]
	v_mfma_f32_16x16x32_bf16 v[28:31], v[158:161], v[208:211], v[28:31]
	v_mfma_f32_16x16x32_bf16 v[20:23], v[150:153], v[220:223], v[20:23]
	v_mfma_f32_16x16x32_bf16 v[12:15], v[158:161], v[220:223], v[12:15]
	v_mfma_f32_16x16x32_bf16 v[50:53], v[162:165], v[188:191], v[50:53]
	v_mfma_f32_16x16x32_bf16 v[42:45], v[180:183], v[188:191], v[42:45]
	v_mfma_f32_16x16x32_bf16 v[34:37], v[162:165], v[196:199], v[34:37]
	v_mfma_f32_16x16x32_bf16 v[24:27], v[180:183], v[196:199], v[24:27]
	v_mfma_f32_16x16x32_bf16 v[16:19], v[162:165], v[204:207], v[16:19]
	v_mfma_f32_16x16x32_bf16 v[8:11], v[180:183], v[204:207], v[8:11]
	v_mfma_f32_16x16x32_bf16 v[4:7], v[162:165], v[212:215], v[4:7]
	v_mfma_f32_16x16x32_bf16 v[0:3], v[180:183], v[212:215], v[0:3]
	v_mfma_f32_16x16x32_bf16 v[50:53], v[176:179], v[192:195], v[50:53]
	v_mfma_f32_16x16x32_bf16 v[42:45], v[184:187], v[192:195], v[42:45]
	v_mfma_f32_16x16x32_bf16 v[34:37], v[176:179], v[200:203], v[34:37]
	v_mfma_f32_16x16x32_bf16 v[24:27], v[184:187], v[200:203], v[24:27]
	v_mfma_f32_16x16x32_bf16 v[16:19], v[176:179], v[208:211], v[16:19]
	v_mfma_f32_16x16x32_bf16 v[8:11], v[184:187], v[208:211], v[8:11]
	v_mfma_f32_16x16x32_bf16 v[4:7], v[176:179], v[220:223], v[4:7]
	v_mfma_f32_16x16x32_bf16 v[0:3], v[184:187], v[220:223], v[0:3]
	s_barrier
	s_add_i32 s67, 0, 0x18000
	v_add_u32_e32 v145, s67, v143
	s_add_i32 s69, 0, 0x1c000
	ds_read_b128 v[146:149], v145
	ds_read_b128 v[150:153], v145 offset:1024
	ds_read_b128 v[154:157], v145 offset:2048
	ds_read_b128 v[158:161], v145 offset:3072
	v_add_u32_e32 v145, s69, v143
	ds_read_b128 v[162:165], v145
	ds_read_b128 v[176:179], v145 offset:1024
	ds_read_b128 v[180:183], v145 offset:2048
	ds_read_b128 v[184:187], v145 offset:3072
	s_add_u32 s54, s54, 0x40000
	s_addc_u32 s55, s55, 0
	s_mov_b32 m0, s39
	ds_read_b128 v[188:191], v144 offset:32768
	ds_read_b128 v[192:195], v144 offset:33792
	ds_read_b128 v[196:199], v144 offset:34816
	ds_read_b128 v[200:203], v144 offset:35840
	ds_read_b128 v[204:207], v144 offset:36864
	ds_read_b128 v[208:211], v144 offset:37888
	ds_read_b128 v[212:215], v144 offset:38912
	ds_read_b128 v[220:223], v144 offset:39936
	global_load_lds_dwordx4 v130, s[54:55]
	s_mov_b32 m0, s46
	s_nop 0
	global_load_lds_dwordx4 v132, s[54:55]
	s_waitcnt vmcnt(8)
	s_waitcnt lgkmcnt(0)
	s_barrier
	v_mfma_f32_16x16x32_bf16 v[126:129], v[146:149], v[188:191], v[126:129]
	v_mfma_f32_16x16x32_bf16 v[122:125], v[154:157], v[188:191], v[122:125]
	v_mfma_f32_16x16x32_bf16 v[118:121], v[146:149], v[196:199], v[118:121]
	v_mfma_f32_16x16x32_bf16 v[110:113], v[154:157], v[196:199], v[110:113]
	v_mfma_f32_16x16x32_bf16 v[102:105], v[146:149], v[204:207], v[102:105]
	v_mfma_f32_16x16x32_bf16 v[94:97], v[154:157], v[204:207], v[94:97]
	v_mfma_f32_16x16x32_bf16 v[86:89], v[146:149], v[212:215], v[86:89]
	v_mfma_f32_16x16x32_bf16 v[78:81], v[154:157], v[212:215], v[78:81]
	v_mfma_f32_16x16x32_bf16 v[126:129], v[150:153], v[192:195], v[126:129]
	v_mfma_f32_16x16x32_bf16 v[122:125], v[158:161], v[192:195], v[122:125]
	v_mfma_f32_16x16x32_bf16 v[118:121], v[150:153], v[200:203], v[118:121]
	v_mfma_f32_16x16x32_bf16 v[110:113], v[158:161], v[200:203], v[110:113]
	v_mfma_f32_16x16x32_bf16 v[102:105], v[150:153], v[208:211], v[102:105]
	v_mfma_f32_16x16x32_bf16 v[94:97], v[158:161], v[208:211], v[94:97]
	v_mfma_f32_16x16x32_bf16 v[86:89], v[150:153], v[220:223], v[86:89]
	v_mfma_f32_16x16x32_bf16 v[78:81], v[158:161], v[220:223], v[78:81]
	v_mfma_f32_16x16x32_bf16 v[114:117], v[162:165], v[188:191], v[114:117]
	v_mfma_f32_16x16x32_bf16 v[106:109], v[180:183], v[188:191], v[106:109]
	v_mfma_f32_16x16x32_bf16 v[98:101], v[162:165], v[196:199], v[98:101]
	v_mfma_f32_16x16x32_bf16 v[90:93], v[180:183], v[196:199], v[90:93]
	v_mfma_f32_16x16x32_bf16 v[82:85], v[162:165], v[204:207], v[82:85]
	v_mfma_f32_16x16x32_bf16 v[74:77], v[180:183], v[204:207], v[74:77]
	v_mfma_f32_16x16x32_bf16 v[70:73], v[162:165], v[212:215], v[70:73]
	v_mfma_f32_16x16x32_bf16 v[66:69], v[180:183], v[212:215], v[66:69]
	v_mfma_f32_16x16x32_bf16 v[114:117], v[176:179], v[192:195], v[114:117]
	v_mfma_f32_16x16x32_bf16 v[106:109], v[184:187], v[192:195], v[106:109]
	v_mfma_f32_16x16x32_bf16 v[98:101], v[176:179], v[200:203], v[98:101]
	v_mfma_f32_16x16x32_bf16 v[90:93], v[184:187], v[200:203], v[90:93]
	v_mfma_f32_16x16x32_bf16 v[82:85], v[176:179], v[208:211], v[82:85]
	v_mfma_f32_16x16x32_bf16 v[74:77], v[184:187], v[208:211], v[74:77]
	v_mfma_f32_16x16x32_bf16 v[70:73], v[176:179], v[220:223], v[70:73]
	v_mfma_f32_16x16x32_bf16 v[66:69], v[184:187], v[220:223], v[66:69]
	s_barrier
	s_add_i32 s54, s67, s13
	s_mov_b32 m0, s54
	ds_read_b128 v[188:191], v144 offset:49152
	ds_read_b128 v[192:195], v144 offset:50176
	ds_read_b128 v[196:199], v144 offset:51200
	ds_read_b128 v[200:203], v144 offset:52224
	ds_read_b128 v[204:207], v144 offset:53248
	ds_read_b128 v[208:211], v144 offset:54272
	ds_read_b128 v[212:215], v144 offset:55296
	ds_read_b128 v[220:223], v144 offset:56320
	global_load_lds_dwordx4 v32, s[98:99]
	s_add_i32 m0, s54, 0x2000
	s_add_u32 s52, s52, 0x40080
	s_addc_u32 s53, s53, 0
	s_add_i32 s54, s69, s13
	global_load_lds_dwordx4 v134, s[98:99]
	s_mov_b32 m0, s54
	s_nop 0
	global_load_lds_dwordx4 v32, s[52:53]
	s_add_i32 m0, s54, 0x2000
	s_nop 0
	global_load_lds_dwordx4 v134, s[52:53]
	s_mov_b32 m0, s57
	s_nop 0
	global_load_lds_dwordx4 v130, s[100:101]
	s_mov_b32 m0, s58
	s_nop 0
	global_load_lds_dwordx4 v132, s[100:101]
	s_waitcnt vmcnt(8)
	s_waitcnt lgkmcnt(0)
	s_barrier
	v_mfma_f32_16x16x32_bf16 v[62:65], v[146:149], v[188:191], v[62:65]
	v_mfma_f32_16x16x32_bf16 v[58:61], v[154:157], v[188:191], v[58:61]
	s_add_u32 s50, s50, 0x100
	s_addc_u32 s51, s51, 0
	s_add_u32 s64, s64, 0x100
	s_addc_u32 s65, s65, 0
	s_cmp_ge_i32 s66, s61
	s_mov_b32 s52, s66
	v_mfma_f32_16x16x32_bf16 v[54:57], v[146:149], v[196:199], v[54:57]
	v_mfma_f32_16x16x32_bf16 v[46:49], v[154:157], v[196:199], v[46:49]
	v_mfma_f32_16x16x32_bf16 v[38:41], v[146:149], v[204:207], v[38:41]
	v_mfma_f32_16x16x32_bf16 v[28:31], v[154:157], v[204:207], v[28:31]
	v_mfma_f32_16x16x32_bf16 v[20:23], v[146:149], v[212:215], v[20:23]
	v_mfma_f32_16x16x32_bf16 v[12:15], v[154:157], v[212:215], v[12:15]
	v_mfma_f32_16x16x32_bf16 v[62:65], v[150:153], v[192:195], v[62:65]
	v_mfma_f32_16x16x32_bf16 v[58:61], v[158:161], v[192:195], v[58:61]
	v_mfma_f32_16x16x32_bf16 v[54:57], v[150:153], v[200:203], v[54:57]
	v_mfma_f32_16x16x32_bf16 v[46:49], v[158:161], v[200:203], v[46:49]
	v_mfma_f32_16x16x32_bf16 v[38:41], v[150:153], v[208:211], v[38:41]
	v_mfma_f32_16x16x32_bf16 v[28:31], v[158:161], v[208:211], v[28:31]
	v_mfma_f32_16x16x32_bf16 v[20:23], v[150:153], v[220:223], v[20:23]
	v_mfma_f32_16x16x32_bf16 v[12:15], v[158:161], v[220:223], v[12:15]
	v_mfma_f32_16x16x32_bf16 v[50:53], v[162:165], v[188:191], v[50:53]
	v_mfma_f32_16x16x32_bf16 v[42:45], v[180:183], v[188:191], v[42:45]
	v_mfma_f32_16x16x32_bf16 v[34:37], v[162:165], v[196:199], v[34:37]
	v_mfma_f32_16x16x32_bf16 v[24:27], v[180:183], v[196:199], v[24:27]
	v_mfma_f32_16x16x32_bf16 v[16:19], v[162:165], v[204:207], v[16:19]
	v_mfma_f32_16x16x32_bf16 v[8:11], v[180:183], v[204:207], v[8:11]
	v_mfma_f32_16x16x32_bf16 v[4:7], v[162:165], v[212:215], v[4:7]
	v_mfma_f32_16x16x32_bf16 v[0:3], v[180:183], v[212:215], v[0:3]
	v_mfma_f32_16x16x32_bf16 v[50:53], v[176:179], v[192:195], v[50:53]
	v_mfma_f32_16x16x32_bf16 v[42:45], v[184:187], v[192:195], v[42:45]
	v_mfma_f32_16x16x32_bf16 v[34:37], v[176:179], v[200:203], v[34:37]
	v_mfma_f32_16x16x32_bf16 v[24:27], v[184:187], v[200:203], v[24:27]
	v_mfma_f32_16x16x32_bf16 v[16:19], v[176:179], v[208:211], v[16:19]
	v_mfma_f32_16x16x32_bf16 v[8:11], v[184:187], v[208:211], v[8:11]
	v_mfma_f32_16x16x32_bf16 v[4:7], v[176:179], v[220:223], v[4:7]
	v_mfma_f32_16x16x32_bf16 v[0:3], v[184:187], v[220:223], v[0:3]
	s_barrier
	s_cbranch_scc0 .LBB0_333
	s_and_b64 vcc, exec, s[20:21]
	s_cbranch_vccz .LBB0_336
	s_barrier

.LBB0_381:
	s_add_i32 s42, s24, 2
	s_add_u32 s0, s20, 0xfffc0080
	s_addc_u32 s25, s21, -1
	s_add_i32 s90, 0, 0x10000
	s_cmp_eq_u32 s1, s24
	s_cselect_b32 s27, s61, s25
	s_cselect_b32 s26, s60, s0
	s_cselect_b32 s25, s63, s23
	s_cselect_b32 s24, s62, s22
	s_add_i32 s33, 0, 0x14000
	v_add_u32_e32 v172, s90, v169
	v_add_u32_e32 v174, s33, v169
	ds_read_b128 v[130:133], v172
	ds_read_b128 v[134:137], v172 offset:1024
	ds_read_b128 v[152:155], v172 offset:2048
	ds_read_b128 v[156:159], v172 offset:3072
	ds_read_b128 v[160:163], v174
	ds_read_b128 v[176:179], v174 offset:1024
	ds_read_b128 v[180:183], v174 offset:2048
	ds_read_b128 v[184:187], v174 offset:3072
	s_add_i32 s59, s77, 0xc000
	s_mov_b32 m0, s59
	s_add_i32 s89, s77, 0xe000
	ds_read_b128 v[188:191], v170
	ds_read_b128 v[192:195], v170 offset:1024
	ds_read_b128 v[196:199], v170 offset:2048
	ds_read_b128 v[200:203], v170 offset:3072
	ds_read_b128 v[204:207], v170 offset:4096
	ds_read_b128 v[208:211], v170 offset:5120
	ds_read_b128 v[212:215], v170 offset:6144
	ds_read_b128 v[220:223], v170 offset:7168
	global_load_lds_dwordx4 v144, s[20:21]
	s_mov_b32 m0, s89
	s_nop 0
	global_load_lds_dwordx4 v146, s[20:21]
	s_waitcnt vmcnt(8)
	s_waitcnt lgkmcnt(0)
	s_barrier
	v_mfma_f32_16x16x32_bf16 v[0:3], v[130:133], v[188:191], v[0:3]
	v_mfma_f32_16x16x32_bf16 v[4:7], v[152:155], v[188:191], v[4:7]
	v_mfma_f32_16x16x32_bf16 v[16:19], v[130:133], v[196:199], v[16:19]
	v_mfma_f32_16x16x32_bf16 v[20:23], v[152:155], v[196:199], v[20:23]
	v_mfma_f32_16x16x32_bf16 v[46:49], v[130:133], v[204:207], v[46:49]
	v_mfma_f32_16x16x32_bf16 v[50:53], v[152:155], v[204:207], v[50:53]
	v_mfma_f32_16x16x32_bf16 v[66:69], v[130:133], v[212:215], v[66:69]
	v_mfma_f32_16x16x32_bf16 v[70:73], v[152:155], v[212:215], v[70:73]
	v_mfma_f32_16x16x32_bf16 v[0:3], v[134:137], v[192:195], v[0:3]
	v_mfma_f32_16x16x32_bf16 v[4:7], v[156:159], v[192:195], v[4:7]
	v_mfma_f32_16x16x32_bf16 v[16:19], v[134:137], v[200:203], v[16:19]
	v_mfma_f32_16x16x32_bf16 v[20:23], v[156:159], v[200:203], v[20:23]
	v_mfma_f32_16x16x32_bf16 v[46:49], v[134:137], v[208:211], v[46:49]
	v_mfma_f32_16x16x32_bf16 v[50:53], v[156:159], v[208:211], v[50:53]
	v_mfma_f32_16x16x32_bf16 v[66:69], v[134:137], v[220:223], v[66:69]
	v_mfma_f32_16x16x32_bf16 v[70:73], v[156:159], v[220:223], v[70:73]
	v_mfma_f32_16x16x32_bf16 v[8:11], v[160:163], v[188:191], v[8:11]
	v_mfma_f32_16x16x32_bf16 v[12:15], v[180:183], v[188:191], v[12:15]
	v_mfma_f32_16x16x32_bf16 v[24:27], v[160:163], v[196:199], v[24:27]
	v_mfma_f32_16x16x32_bf16 v[28:31], v[180:183], v[196:199], v[28:31]
	v_mfma_f32_16x16x32_bf16 v[54:57], v[160:163], v[204:207], v[54:57]
	v_mfma_f32_16x16x32_bf16 v[58:61], v[180:183], v[204:207], v[58:61]
	v_mfma_f32_16x16x32_bf16 v[74:77], v[160:163], v[212:215], v[74:77]
	v_mfma_f32_16x16x32_bf16 v[78:81], v[180:183], v[212:215], v[78:81]
	v_mfma_f32_16x16x32_bf16 v[8:11], v[176:179], v[192:195], v[8:11]
	v_mfma_f32_16x16x32_bf16 v[12:15], v[184:187], v[192:195], v[12:15]
	v_mfma_f32_16x16x32_bf16 v[24:27], v[176:179], v[200:203], v[24:27]
	v_mfma_f32_16x16x32_bf16 v[28:31], v[184:187], v[200:203], v[28:31]
	v_mfma_f32_16x16x32_bf16 v[54:57], v[176:179], v[208:211], v[54:57]
	v_mfma_f32_16x16x32_bf16 v[58:61], v[184:187], v[208:211], v[58:61]
	v_mfma_f32_16x16x32_bf16 v[74:77], v[176:179], v[220:223], v[74:77]
	v_mfma_f32_16x16x32_bf16 v[78:81], v[184:187], v[220:223], v[78:81]
	s_barrier
	s_add_u32 s98, s24, s28
	s_addc_u32 s99, s25, s29
	s_add_u32 s100, s26, s28
	s_addc_u32 s101, s27, s29
	s_add_i32 s90, s90, s69
	s_add_i32 s91, s90, 0x2000
	s_mov_b32 m0, s90
	s_add_u32 s38, s24, 0x40000
	ds_read_b128 v[188:191], v170 offset:16384
	ds_read_b128 v[192:195], v170 offset:17408
	ds_read_b128 v[196:199], v170 offset:18432
	ds_read_b128 v[200:203], v170 offset:19456
	ds_read_b128 v[204:207], v170 offset:20480
	ds_read_b128 v[208:211], v170 offset:21504
	ds_read_b128 v[212:215], v170 offset:22528
	ds_read_b128 v[220:223], v170 offset:23552
	global_load_lds_dwordx4 v32, s[24:25]
	s_mov_b32 m0, s91
	s_addc_u32 s39, s25, 0
	s_add_i32 s33, s33, s69
	global_load_lds_dwordx4 v142, s[24:25]
	s_mov_b32 m0, s33
	s_nop 0
	global_load_lds_dwordx4 v32, s[38:39]
	s_add_i32 m0, s33, 0x2000
	s_nop 0
	global_load_lds_dwordx4 v142, s[38:39]
	s_add_i32 s38, s33, 0x2000
	s_mov_b32 m0, s77
	s_nop 0
	global_load_lds_dwordx4 v138, s[26:27]
	s_mov_b32 m0, s13
	s_nop 0
	global_load_lds_dwordx4 v140, s[26:27]
	s_waitcnt vmcnt(8)
	s_waitcnt lgkmcnt(0)
	s_barrier
	v_mfma_f32_16x16x32_bf16 v[82:85], v[130:133], v[188:191], v[82:85]
	v_mfma_f32_16x16x32_bf16 v[86:89], v[152:155], v[188:191], v[86:89]
	v_mfma_f32_16x16x32_bf16 v[106:109], v[130:133], v[196:199], v[106:109]
	v_mfma_f32_16x16x32_bf16 v[114:117], v[152:155], v[196:199], v[114:117]
	v_mfma_f32_16x16x32_bf16 v[126:129], v[130:133], v[204:207], v[126:129]
	v_mfma_f32_16x16x32_bf16 v[110:113], v[152:155], v[204:207], v[110:113]
	v_mfma_f32_16x16x32_bf16 v[62:65], v[130:133], v[212:215], v[62:65]
	v_mfma_f32_16x16x32_bf16 v[42:45], v[152:155], v[212:215], v[42:45]
	v_mfma_f32_16x16x32_bf16 v[82:85], v[134:137], v[192:195], v[82:85]
	v_mfma_f32_16x16x32_bf16 v[86:89], v[156:159], v[192:195], v[86:89]
	v_mfma_f32_16x16x32_bf16 v[106:109], v[134:137], v[200:203], v[106:109]
	v_mfma_f32_16x16x32_bf16 v[114:117], v[156:159], v[200:203], v[114:117]
	v_mfma_f32_16x16x32_bf16 v[126:129], v[134:137], v[208:211], v[126:129]
	v_mfma_f32_16x16x32_bf16 v[110:113], v[156:159], v[208:211], v[110:113]
	v_mfma_f32_16x16x32_bf16 v[62:65], v[134:137], v[220:223], v[62:65]
	v_mfma_f32_16x16x32_bf16 v[42:45], v[156:159], v[220:223], v[42:45]
	v_mfma_f32_16x16x32_bf16 v[90:93], v[160:163], v[188:191], v[90:93]
	v_mfma_f32_16x16x32_bf16 v[94:97], v[180:183], v[188:191], v[94:97]
	v_mfma_f32_16x16x32_bf16 v[118:121], v[160:163], v[196:199], v[118:121]
	v_mfma_f32_16x16x32_bf16 v[122:125], v[180:183], v[196:199], v[122:125]
	v_mfma_f32_16x16x32_bf16 v[102:105], v[160:163], v[204:207], v[102:105]
	v_mfma_f32_16x16x32_bf16 v[98:101], v[180:183], v[204:207], v[98:101]
	v_mfma_f32_16x16x32_bf16 v[38:41], v[160:163], v[212:215], v[38:41]
	v_mfma_f32_16x16x32_bf16 v[34:37], v[180:183], v[212:215], v[34:37]
	v_mfma_f32_16x16x32_bf16 v[90:93], v[176:179], v[192:195], v[90:93]
	v_mfma_f32_16x16x32_bf16 v[94:97], v[184:187], v[192:195], v[94:97]
	v_mfma_f32_16x16x32_bf16 v[118:121], v[176:179], v[200:203], v[118:121]
	v_mfma_f32_16x16x32_bf16 v[122:125], v[184:187], v[200:203], v[122:125]
	v_mfma_f32_16x16x32_bf16 v[102:105], v[176:179], v[208:211], v[102:105]
	v_mfma_f32_16x16x32_bf16 v[98:101], v[184:187], v[208:211], v[98:101]
	v_mfma_f32_16x16x32_bf16 v[38:41], v[176:179], v[220:223], v[38:41]
	v_mfma_f32_16x16x32_bf16 v[34:37], v[184:187], v[220:223], v[34:37]
	s_barrier
	s_add_i32 s39, 0, 0x18000
	s_add_i32 s65, 0, 0x1c000
	v_add_u32_e32 v176, s39, v169
	v_add_u32_e32 v177, s65, v169
	ds_read_b128 v[130:133], v176
	ds_read_b128 v[134:137], v176 offset:1024
	ds_read_b128 v[152:155], v176 offset:2048
	ds_read_b128 v[156:159], v176 offset:3072
	ds_read_b128 v[160:163], v177
	ds_read_b128 v[178:181], v177 offset:1024
	ds_read_b128 v[182:185], v177 offset:2048
	ds_read_b128 v[186:189], v177 offset:3072
	s_add_u32 s26, s26, 0x40000
	s_addc_u32 s27, s27, 0
	s_mov_b32 m0, s78
	ds_read_b128 v[190:193], v170 offset:32768
	ds_read_b128 v[194:197], v170 offset:33792
	ds_read_b128 v[198:201], v170 offset:34816
	ds_read_b128 v[202:205], v170 offset:35840
	ds_read_b128 v[206:209], v170 offset:36864
	ds_read_b128 v[210:213], v170 offset:37888
	ds_read_b128 v[220:223], v170 offset:38912
	ds_read_b128 v[224:227], v170 offset:39936
	global_load_lds_dwordx4 v138, s[26:27]
	s_mov_b32 m0, s12
	s_nop 0
	global_load_lds_dwordx4 v140, s[26:27]
	s_waitcnt vmcnt(8)
	s_waitcnt lgkmcnt(0)
	s_barrier
	v_mfma_f32_16x16x32_bf16 v[0:3], v[130:133], v[190:193], v[0:3]
	v_mfma_f32_16x16x32_bf16 v[4:7], v[152:155], v[190:193], v[4:7]
	v_mfma_f32_16x16x32_bf16 v[16:19], v[130:133], v[198:201], v[16:19]
	v_mfma_f32_16x16x32_bf16 v[20:23], v[152:155], v[198:201], v[20:23]
	v_mfma_f32_16x16x32_bf16 v[46:49], v[130:133], v[206:209], v[46:49]
	v_mfma_f32_16x16x32_bf16 v[50:53], v[152:155], v[206:209], v[50:53]
	v_mfma_f32_16x16x32_bf16 v[66:69], v[130:133], v[220:223], v[66:69]
	v_mfma_f32_16x16x32_bf16 v[70:73], v[152:155], v[220:223], v[70:73]
	v_mfma_f32_16x16x32_bf16 v[0:3], v[134:137], v[194:197], v[0:3]
	v_mfma_f32_16x16x32_bf16 v[4:7], v[156:159], v[194:197], v[4:7]
	v_mfma_f32_16x16x32_bf16 v[16:19], v[134:137], v[202:205], v[16:19]
	v_mfma_f32_16x16x32_bf16 v[20:23], v[156:159], v[202:205], v[20:23]
	v_mfma_f32_16x16x32_bf16 v[46:49], v[134:137], v[210:213], v[46:49]
	v_mfma_f32_16x16x32_bf16 v[50:53], v[156:159], v[210:213], v[50:53]
	v_mfma_f32_16x16x32_bf16 v[66:69], v[134:137], v[224:227], v[66:69]
	v_mfma_f32_16x16x32_bf16 v[70:73], v[156:159], v[224:227], v[70:73]
	v_mfma_f32_16x16x32_bf16 v[8:11], v[160:163], v[190:193], v[8:11]
	v_mfma_f32_16x16x32_bf16 v[12:15], v[182:185], v[190:193], v[12:15]
	v_mfma_f32_16x16x32_bf16 v[24:27], v[160:163], v[198:201], v[24:27]
	v_mfma_f32_16x16x32_bf16 v[28:31], v[182:185], v[198:201], v[28:31]
	v_mfma_f32_16x16x32_bf16 v[54:57], v[160:163], v[206:209], v[54:57]
	v_mfma_f32_16x16x32_bf16 v[58:61], v[182:185], v[206:209], v[58:61]
	v_mfma_f32_16x16x32_bf16 v[74:77], v[160:163], v[220:223], v[74:77]
	v_mfma_f32_16x16x32_bf16 v[78:81], v[182:185], v[220:223], v[78:81]
	v_mfma_f32_16x16x32_bf16 v[8:11], v[178:181], v[194:197], v[8:11]
	v_mfma_f32_16x16x32_bf16 v[12:15], v[186:189], v[194:197], v[12:15]
	v_mfma_f32_16x16x32_bf16 v[24:27], v[178:181], v[202:205], v[24:27]
	v_mfma_f32_16x16x32_bf16 v[28:31], v[186:189], v[202:205], v[28:31]
	v_mfma_f32_16x16x32_bf16 v[54:57], v[178:181], v[210:213], v[54:57]
	v_mfma_f32_16x16x32_bf16 v[58:61], v[186:189], v[210:213], v[58:61]
	v_mfma_f32_16x16x32_bf16 v[74:77], v[178:181], v[224:227], v[74:77]
	v_mfma_f32_16x16x32_bf16 v[78:81], v[186:189], v[224:227], v[78:81]
	s_barrier
	s_add_i32 s39, s39, s69
	s_add_i32 s64, s39, 0x2000
	s_mov_b32 m0, s39
	s_add_u32 s24, s24, 0x40080
	ds_read_b128 v[190:193], v170 offset:49152
	ds_read_b128 v[194:197], v170 offset:50176
	ds_read_b128 v[198:201], v170 offset:51200
	ds_read_b128 v[202:205], v170 offset:52224
	ds_read_b128 v[206:209], v170 offset:53248
	ds_read_b128 v[210:213], v170 offset:54272
	ds_read_b128 v[220:223], v170 offset:55296
	ds_read_b128 v[224:227], v170 offset:56320
	global_load_lds_dwordx4 v32, s[98:99]
	s_mov_b32 m0, s64
	s_addc_u32 s25, s25, 0
	s_add_i32 s65, s65, s69
	global_load_lds_dwordx4 v142, s[98:99]
	s_mov_b32 m0, s65
	s_add_i32 s0, s65, 0x2000
	global_load_lds_dwordx4 v32, s[24:25]
	s_mov_b32 m0, s0
	s_nop 0
	global_load_lds_dwordx4 v142, s[24:25]
	s_mov_b32 m0, s84
	s_nop 0
	global_load_lds_dwordx4 v138, s[100:101]
	s_mov_b32 m0, s85
	s_nop 0
	global_load_lds_dwordx4 v140, s[100:101]
	s_waitcnt vmcnt(8)
	s_waitcnt lgkmcnt(0)
	s_barrier
	v_mfma_f32_16x16x32_bf16 v[82:85], v[130:133], v[190:193], v[82:85]
	v_mfma_f32_16x16x32_bf16 v[86:89], v[152:155], v[190:193], v[86:89]
	s_add_u32 s20, s20, 0x100
	s_addc_u32 s21, s21, 0
	s_add_u32 s22, s22, 0x100
	s_addc_u32 s23, s23, 0
	s_cmp_ge_i32 s42, s79
	s_mov_b32 s24, s42
	v_mfma_f32_16x16x32_bf16 v[106:109], v[130:133], v[198:201], v[106:109]
	v_mfma_f32_16x16x32_bf16 v[114:117], v[152:155], v[198:201], v[114:117]
	v_mfma_f32_16x16x32_bf16 v[126:129], v[130:133], v[206:209], v[126:129]
	v_mfma_f32_16x16x32_bf16 v[110:113], v[152:155], v[206:209], v[110:113]
	v_mfma_f32_16x16x32_bf16 v[62:65], v[130:133], v[220:223], v[62:65]
	v_mfma_f32_16x16x32_bf16 v[42:45], v[152:155], v[220:223], v[42:45]
	v_mfma_f32_16x16x32_bf16 v[82:85], v[134:137], v[194:197], v[82:85]
	v_mfma_f32_16x16x32_bf16 v[86:89], v[156:159], v[194:197], v[86:89]
	v_mfma_f32_16x16x32_bf16 v[106:109], v[134:137], v[202:205], v[106:109]
	v_mfma_f32_16x16x32_bf16 v[114:117], v[156:159], v[202:205], v[114:117]
	v_mfma_f32_16x16x32_bf16 v[126:129], v[134:137], v[210:213], v[126:129]
	v_mfma_f32_16x16x32_bf16 v[110:113], v[156:159], v[210:213], v[110:113]
	v_mfma_f32_16x16x32_bf16 v[62:65], v[134:137], v[224:227], v[62:65]
	v_mfma_f32_16x16x32_bf16 v[42:45], v[156:159], v[224:227], v[42:45]
	v_mfma_f32_16x16x32_bf16 v[90:93], v[160:163], v[190:193], v[90:93]
	v_mfma_f32_16x16x32_bf16 v[94:97], v[182:185], v[190:193], v[94:97]
	v_mfma_f32_16x16x32_bf16 v[118:121], v[160:163], v[198:201], v[118:121]
	v_mfma_f32_16x16x32_bf16 v[122:125], v[182:185], v[198:201], v[122:125]
	v_mfma_f32_16x16x32_bf16 v[102:105], v[160:163], v[206:209], v[102:105]
	v_mfma_f32_16x16x32_bf16 v[98:101], v[182:185], v[206:209], v[98:101]
	v_mfma_f32_16x16x32_bf16 v[38:41], v[160:163], v[220:223], v[38:41]
	v_mfma_f32_16x16x32_bf16 v[34:37], v[182:185], v[220:223], v[34:37]
	v_mfma_f32_16x16x32_bf16 v[90:93], v[178:181], v[194:197], v[90:93]
	v_mfma_f32_16x16x32_bf16 v[94:97], v[186:189], v[194:197], v[94:97]
	v_mfma_f32_16x16x32_bf16 v[118:121], v[178:181], v[202:205], v[118:121]
	v_mfma_f32_16x16x32_bf16 v[122:125], v[186:189], v[202:205], v[122:125]
	v_mfma_f32_16x16x32_bf16 v[102:105], v[178:181], v[210:213], v[102:105]
	v_mfma_f32_16x16x32_bf16 v[98:101], v[186:189], v[210:213], v[98:101]
	v_mfma_f32_16x16x32_bf16 v[38:41], v[178:181], v[224:227], v[38:41]
	v_mfma_f32_16x16x32_bf16 v[34:37], v[186:189], v[224:227], v[34:37]
	s_barrier
	s_cbranch_scc0 .LBB0_381
	s_and_b64 vcc, exec, s[56:57]
	s_cbranch_vccz .LBB0_384
	s_barrier

.LBB0_405:
	ds_read_b128 v[134:137], v172
	ds_read_b128 v[152:155], v172 offset:1024
	ds_read_b128 v[156:159], v172 offset:2048
	ds_read_b128 v[160:163], v172 offset:3072
	ds_read_b128 v[178:181], v174
	ds_read_b128 v[182:185], v174 offset:1024
	ds_read_b128 v[186:189], v174 offset:2048
	ds_read_b128 v[190:193], v174 offset:3072
	s_add_u32 s26, s60, s24
	s_addc_u32 s27, s61, s25
	s_add_u32 s50, s62, s24
	s_addc_u32 s51, s63, s25
	s_cmp_eq_u32 s87, s49
	s_cselect_b32 s45, s1, s27
	s_cselect_b32 s44, s22, s26
	s_cselect_b32 s27, s23, s51
	s_cselect_b32 s26, s48, s50
	s_mov_b32 m0, s59
	ds_read_b128 v[194:197], v170
	ds_read_b128 v[198:201], v170 offset:1024
	ds_read_b128 v[202:205], v170 offset:2048
	ds_read_b128 v[206:209], v170 offset:3072
	ds_read_b128 v[210:213], v170 offset:4096
	ds_read_b128 v[220:223], v170 offset:5120
	ds_read_b128 v[224:227], v170 offset:6144
	ds_read_b128 v[228:231], v170 offset:7168
	global_load_lds_dwordx4 v132, s[60:61]
	s_mov_b32 m0, s89
	s_nop 0
	global_load_lds_dwordx4 v130, s[60:61]
	s_waitcnt vmcnt(8)
	s_waitcnt lgkmcnt(0)
	s_barrier
	v_mfma_f32_16x16x32_bf16 v[0:3], v[134:137], v[194:197], v[0:3]
	v_mfma_f32_16x16x32_bf16 v[4:7], v[156:159], v[194:197], v[4:7]
	v_mfma_f32_16x16x32_bf16 v[16:19], v[134:137], v[202:205], v[16:19]
	v_mfma_f32_16x16x32_bf16 v[20:23], v[156:159], v[202:205], v[20:23]
	v_mfma_f32_16x16x32_bf16 v[46:49], v[134:137], v[210:213], v[46:49]
	v_mfma_f32_16x16x32_bf16 v[50:53], v[156:159], v[210:213], v[50:53]
	v_mfma_f32_16x16x32_bf16 v[66:69], v[134:137], v[224:227], v[66:69]
	v_mfma_f32_16x16x32_bf16 v[70:73], v[156:159], v[224:227], v[70:73]
	v_mfma_f32_16x16x32_bf16 v[0:3], v[152:155], v[198:201], v[0:3]
	v_mfma_f32_16x16x32_bf16 v[4:7], v[160:163], v[198:201], v[4:7]
	v_mfma_f32_16x16x32_bf16 v[16:19], v[152:155], v[206:209], v[16:19]
	v_mfma_f32_16x16x32_bf16 v[20:23], v[160:163], v[206:209], v[20:23]
	v_mfma_f32_16x16x32_bf16 v[46:49], v[152:155], v[220:223], v[46:49]
	v_mfma_f32_16x16x32_bf16 v[50:53], v[160:163], v[220:223], v[50:53]
	v_mfma_f32_16x16x32_bf16 v[66:69], v[152:155], v[228:231], v[66:69]
	v_mfma_f32_16x16x32_bf16 v[70:73], v[160:163], v[228:231], v[70:73]
	v_mfma_f32_16x16x32_bf16 v[8:11], v[178:181], v[194:197], v[8:11]
	v_mfma_f32_16x16x32_bf16 v[12:15], v[186:189], v[194:197], v[12:15]
	v_mfma_f32_16x16x32_bf16 v[24:27], v[178:181], v[202:205], v[24:27]
	v_mfma_f32_16x16x32_bf16 v[28:31], v[186:189], v[202:205], v[28:31]
	v_mfma_f32_16x16x32_bf16 v[54:57], v[178:181], v[210:213], v[54:57]
	v_mfma_f32_16x16x32_bf16 v[58:61], v[186:189], v[210:213], v[58:61]
	v_mfma_f32_16x16x32_bf16 v[74:77], v[178:181], v[224:227], v[74:77]
	v_mfma_f32_16x16x32_bf16 v[78:81], v[186:189], v[224:227], v[78:81]
	v_mfma_f32_16x16x32_bf16 v[8:11], v[182:185], v[198:201], v[8:11]
	v_mfma_f32_16x16x32_bf16 v[12:15], v[190:193], v[198:201], v[12:15]
	v_mfma_f32_16x16x32_bf16 v[24:27], v[182:185], v[206:209], v[24:27]
	v_mfma_f32_16x16x32_bf16 v[28:31], v[190:193], v[206:209], v[28:31]
	v_mfma_f32_16x16x32_bf16 v[54:57], v[182:185], v[220:223], v[54:57]
	v_mfma_f32_16x16x32_bf16 v[58:61], v[190:193], v[220:223], v[58:61]
	v_mfma_f32_16x16x32_bf16 v[74:77], v[182:185], v[228:231], v[74:77]
	v_mfma_f32_16x16x32_bf16 v[78:81], v[190:193], v[228:231], v[78:81]
	s_barrier
	s_add_u32 s98, s26, s28
	s_addc_u32 s99, s27, s29
	s_add_u32 s100, s44, s28
	s_addc_u32 s101, s45, s29
	s_mov_b32 m0, s90
	s_add_u32 s50, s26, 0x40000
	ds_read_b128 v[194:197], v170 offset:16384
	ds_read_b128 v[198:201], v170 offset:17408
	ds_read_b128 v[202:205], v170 offset:18432
	ds_read_b128 v[206:209], v170 offset:19456
	ds_read_b128 v[210:213], v170 offset:20480
	ds_read_b128 v[220:223], v170 offset:21504
	ds_read_b128 v[224:227], v170 offset:22528
	ds_read_b128 v[228:231], v170 offset:23552
	global_load_lds_dwordx4 v32, s[26:27]
	s_mov_b32 m0, s91
	s_addc_u32 s51, s27, 0
	global_load_lds_dwordx4 v142, s[26:27]
	s_mov_b32 m0, s33
	s_nop 0
	global_load_lds_dwordx4 v32, s[50:51]
	s_mov_b32 m0, s38
	s_nop 0
	global_load_lds_dwordx4 v142, s[50:51]
	s_mov_b32 m0, s77
	s_nop 0
	global_load_lds_dwordx4 v138, s[44:45]
	s_mov_b32 m0, s13
	s_nop 0
	global_load_lds_dwordx4 v140, s[44:45]
	s_waitcnt vmcnt(8)
	s_waitcnt lgkmcnt(0)
	s_barrier
	v_mfma_f32_16x16x32_bf16 v[82:85], v[134:137], v[194:197], v[82:85]
	v_mfma_f32_16x16x32_bf16 v[86:89], v[156:159], v[194:197], v[86:89]
	v_mfma_f32_16x16x32_bf16 v[106:109], v[134:137], v[202:205], v[106:109]
	v_mfma_f32_16x16x32_bf16 v[114:117], v[156:159], v[202:205], v[114:117]
	v_mfma_f32_16x16x32_bf16 v[126:129], v[134:137], v[210:213], v[126:129]
	v_mfma_f32_16x16x32_bf16 v[110:113], v[156:159], v[210:213], v[110:113]
	v_mfma_f32_16x16x32_bf16 v[62:65], v[134:137], v[224:227], v[62:65]
	v_mfma_f32_16x16x32_bf16 v[42:45], v[156:159], v[224:227], v[42:45]
	v_mfma_f32_16x16x32_bf16 v[82:85], v[152:155], v[198:201], v[82:85]
	v_mfma_f32_16x16x32_bf16 v[86:89], v[160:163], v[198:201], v[86:89]
	v_mfma_f32_16x16x32_bf16 v[106:109], v[152:155], v[206:209], v[106:109]
	v_mfma_f32_16x16x32_bf16 v[114:117], v[160:163], v[206:209], v[114:117]
	v_mfma_f32_16x16x32_bf16 v[126:129], v[152:155], v[220:223], v[126:129]
	v_mfma_f32_16x16x32_bf16 v[110:113], v[160:163], v[220:223], v[110:113]
	v_mfma_f32_16x16x32_bf16 v[62:65], v[152:155], v[228:231], v[62:65]
	v_mfma_f32_16x16x32_bf16 v[42:45], v[160:163], v[228:231], v[42:45]
	v_mfma_f32_16x16x32_bf16 v[90:93], v[178:181], v[194:197], v[90:93]
	v_mfma_f32_16x16x32_bf16 v[94:97], v[186:189], v[194:197], v[94:97]
	v_mfma_f32_16x16x32_bf16 v[118:121], v[178:181], v[202:205], v[118:121]
	v_mfma_f32_16x16x32_bf16 v[122:125], v[186:189], v[202:205], v[122:125]
	v_mfma_f32_16x16x32_bf16 v[102:105], v[178:181], v[210:213], v[102:105]
	v_mfma_f32_16x16x32_bf16 v[98:101], v[186:189], v[210:213], v[98:101]
	v_mfma_f32_16x16x32_bf16 v[38:41], v[178:181], v[224:227], v[38:41]
	v_mfma_f32_16x16x32_bf16 v[34:37], v[186:189], v[224:227], v[34:37]
	v_mfma_f32_16x16x32_bf16 v[90:93], v[182:185], v[198:201], v[90:93]
	v_mfma_f32_16x16x32_bf16 v[94:97], v[190:193], v[198:201], v[94:97]
	v_mfma_f32_16x16x32_bf16 v[118:121], v[182:185], v[206:209], v[118:121]
	v_mfma_f32_16x16x32_bf16 v[122:125], v[190:193], v[206:209], v[122:125]
	v_mfma_f32_16x16x32_bf16 v[102:105], v[182:185], v[220:223], v[102:105]
	v_mfma_f32_16x16x32_bf16 v[98:101], v[190:193], v[220:223], v[98:101]
	v_mfma_f32_16x16x32_bf16 v[38:41], v[182:185], v[228:231], v[38:41]
	v_mfma_f32_16x16x32_bf16 v[34:37], v[190:193], v[228:231], v[34:37]
	s_barrier
	ds_read_b128 v[134:137], v176
	ds_read_b128 v[152:155], v176 offset:1024
	ds_read_b128 v[156:159], v176 offset:2048
	ds_read_b128 v[160:163], v176 offset:3072
	ds_read_b128 v[178:181], v177
	ds_read_b128 v[182:185], v177 offset:1024
	ds_read_b128 v[186:189], v177 offset:2048
	ds_read_b128 v[190:193], v177 offset:3072
	s_add_u32 s44, s44, 0x40000
	s_addc_u32 s45, s45, 0
	s_mov_b32 m0, s78
	ds_read_b128 v[194:197], v170 offset:32768
	ds_read_b128 v[198:201], v170 offset:33792
	ds_read_b128 v[202:205], v170 offset:34816
	ds_read_b128 v[206:209], v170 offset:35840
	ds_read_b128 v[210:213], v170 offset:36864
	ds_read_b128 v[220:223], v170 offset:37888
	ds_read_b128 v[224:227], v170 offset:38912
	ds_read_b128 v[228:231], v170 offset:39936
	global_load_lds_dwordx4 v138, s[44:45]
	s_mov_b32 m0, s12
	s_nop 0
	global_load_lds_dwordx4 v140, s[44:45]
	s_waitcnt vmcnt(8)
	s_waitcnt lgkmcnt(0)
	s_barrier
	v_mfma_f32_16x16x32_bf16 v[0:3], v[134:137], v[194:197], v[0:3]
	v_mfma_f32_16x16x32_bf16 v[4:7], v[156:159], v[194:197], v[4:7]
	v_mfma_f32_16x16x32_bf16 v[16:19], v[134:137], v[202:205], v[16:19]
	v_mfma_f32_16x16x32_bf16 v[20:23], v[156:159], v[202:205], v[20:23]
	v_mfma_f32_16x16x32_bf16 v[46:49], v[134:137], v[210:213], v[46:49]
	v_mfma_f32_16x16x32_bf16 v[50:53], v[156:159], v[210:213], v[50:53]
	v_mfma_f32_16x16x32_bf16 v[66:69], v[134:137], v[224:227], v[66:69]
	v_mfma_f32_16x16x32_bf16 v[70:73], v[156:159], v[224:227], v[70:73]
	v_mfma_f32_16x16x32_bf16 v[0:3], v[152:155], v[198:201], v[0:3]
	v_mfma_f32_16x16x32_bf16 v[4:7], v[160:163], v[198:201], v[4:7]
	v_mfma_f32_16x16x32_bf16 v[16:19], v[152:155], v[206:209], v[16:19]
	v_mfma_f32_16x16x32_bf16 v[20:23], v[160:163], v[206:209], v[20:23]
	v_mfma_f32_16x16x32_bf16 v[46:49], v[152:155], v[220:223], v[46:49]
	v_mfma_f32_16x16x32_bf16 v[50:53], v[160:163], v[220:223], v[50:53]
	v_mfma_f32_16x16x32_bf16 v[66:69], v[152:155], v[228:231], v[66:69]
	v_mfma_f32_16x16x32_bf16 v[70:73], v[160:163], v[228:231], v[70:73]
	v_mfma_f32_16x16x32_bf16 v[8:11], v[178:181], v[194:197], v[8:11]
	v_mfma_f32_16x16x32_bf16 v[12:15], v[186:189], v[194:197], v[12:15]
	v_mfma_f32_16x16x32_bf16 v[24:27], v[178:181], v[202:205], v[24:27]
	v_mfma_f32_16x16x32_bf16 v[28:31], v[186:189], v[202:205], v[28:31]
	v_mfma_f32_16x16x32_bf16 v[54:57], v[178:181], v[210:213], v[54:57]
	v_mfma_f32_16x16x32_bf16 v[58:61], v[186:189], v[210:213], v[58:61]
	v_mfma_f32_16x16x32_bf16 v[74:77], v[178:181], v[224:227], v[74:77]
	v_mfma_f32_16x16x32_bf16 v[78:81], v[186:189], v[224:227], v[78:81]
	v_mfma_f32_16x16x32_bf16 v[8:11], v[182:185], v[198:201], v[8:11]
	v_mfma_f32_16x16x32_bf16 v[12:15], v[190:193], v[198:201], v[12:15]
	v_mfma_f32_16x16x32_bf16 v[24:27], v[182:185], v[206:209], v[24:27]
	v_mfma_f32_16x16x32_bf16 v[28:31], v[190:193], v[206:209], v[28:31]
	v_mfma_f32_16x16x32_bf16 v[54:57], v[182:185], v[220:223], v[54:57]
	v_mfma_f32_16x16x32_bf16 v[58:61], v[190:193], v[220:223], v[58:61]
	v_mfma_f32_16x16x32_bf16 v[74:77], v[182:185], v[228:231], v[74:77]
	v_mfma_f32_16x16x32_bf16 v[78:81], v[190:193], v[228:231], v[78:81]
	s_barrier
	s_mov_b32 m0, s39
	s_add_u32 s26, s26, 0x40080
	ds_read_b128 v[194:197], v170 offset:49152
	ds_read_b128 v[198:201], v170 offset:50176
	ds_read_b128 v[202:205], v170 offset:51200
	ds_read_b128 v[206:209], v170 offset:52224
	ds_read_b128 v[210:213], v170 offset:53248
	ds_read_b128 v[220:223], v170 offset:54272
	ds_read_b128 v[224:227], v170 offset:55296
	ds_read_b128 v[228:231], v170 offset:56320
	global_load_lds_dwordx4 v32, s[98:99]
	s_mov_b32 m0, s64
	s_addc_u32 s27, s27, 0
	global_load_lds_dwordx4 v142, s[98:99]
	s_mov_b32 m0, s65
	s_nop 0
	global_load_lds_dwordx4 v32, s[26:27]
	s_mov_b32 m0, s0
	s_nop 0
	global_load_lds_dwordx4 v142, s[26:27]
	s_mov_b32 m0, s84
	s_nop 0
	global_load_lds_dwordx4 v138, s[100:101]
	s_mov_b32 m0, s85
	s_nop 0
	global_load_lds_dwordx4 v140, s[100:101]
	s_waitcnt vmcnt(8)
	s_waitcnt lgkmcnt(0)
	s_barrier
	v_mfma_f32_16x16x32_bf16 v[82:85], v[134:137], v[194:197], v[82:85]
	v_mfma_f32_16x16x32_bf16 v[86:89], v[156:159], v[194:197], v[86:89]
	s_add_i32 s26, s49, 2
	s_add_u32 s24, s24, 0x100
	s_addc_u32 s25, s25, 0
	v_lshl_add_u64 v[132:133], v[132:133], 0, s[30:31]
	v_lshl_add_u64 v[130:131], v[130:131], 0, s[30:31]
	s_cmp_ge_i32 s49, s87
	s_mov_b32 s49, s26
	v_mfma_f32_16x16x32_bf16 v[106:109], v[134:137], v[202:205], v[106:109]
	v_mfma_f32_16x16x32_bf16 v[114:117], v[156:159], v[202:205], v[114:117]
	v_mfma_f32_16x16x32_bf16 v[126:129], v[134:137], v[210:213], v[126:129]
	v_mfma_f32_16x16x32_bf16 v[110:113], v[156:159], v[210:213], v[110:113]
	v_mfma_f32_16x16x32_bf16 v[62:65], v[134:137], v[224:227], v[62:65]
	v_mfma_f32_16x16x32_bf16 v[42:45], v[156:159], v[224:227], v[42:45]
	v_mfma_f32_16x16x32_bf16 v[82:85], v[152:155], v[198:201], v[82:85]
	v_mfma_f32_16x16x32_bf16 v[86:89], v[160:163], v[198:201], v[86:89]
	v_mfma_f32_16x16x32_bf16 v[106:109], v[152:155], v[206:209], v[106:109]
	v_mfma_f32_16x16x32_bf16 v[114:117], v[160:163], v[206:209], v[114:117]
	v_mfma_f32_16x16x32_bf16 v[126:129], v[152:155], v[220:223], v[126:129]
	v_mfma_f32_16x16x32_bf16 v[110:113], v[160:163], v[220:223], v[110:113]
	v_mfma_f32_16x16x32_bf16 v[62:65], v[152:155], v[228:231], v[62:65]
	v_mfma_f32_16x16x32_bf16 v[42:45], v[160:163], v[228:231], v[42:45]
	v_mfma_f32_16x16x32_bf16 v[90:93], v[178:181], v[194:197], v[90:93]
	v_mfma_f32_16x16x32_bf16 v[94:97], v[186:189], v[194:197], v[94:97]
	v_mfma_f32_16x16x32_bf16 v[118:121], v[178:181], v[202:205], v[118:121]
	v_mfma_f32_16x16x32_bf16 v[122:125], v[186:189], v[202:205], v[122:125]
	v_mfma_f32_16x16x32_bf16 v[102:105], v[178:181], v[210:213], v[102:105]
	v_mfma_f32_16x16x32_bf16 v[98:101], v[186:189], v[210:213], v[98:101]
	v_mfma_f32_16x16x32_bf16 v[38:41], v[178:181], v[224:227], v[38:41]
	v_mfma_f32_16x16x32_bf16 v[34:37], v[186:189], v[224:227], v[34:37]
	v_mfma_f32_16x16x32_bf16 v[90:93], v[182:185], v[198:201], v[90:93]
	v_mfma_f32_16x16x32_bf16 v[94:97], v[190:193], v[198:201], v[94:97]
	v_mfma_f32_16x16x32_bf16 v[118:121], v[182:185], v[206:209], v[118:121]
	v_mfma_f32_16x16x32_bf16 v[122:125], v[190:193], v[206:209], v[122:125]
	v_mfma_f32_16x16x32_bf16 v[102:105], v[182:185], v[220:223], v[102:105]
	v_mfma_f32_16x16x32_bf16 v[98:101], v[190:193], v[220:223], v[98:101]
	v_mfma_f32_16x16x32_bf16 v[38:41], v[182:185], v[228:231], v[38:41]
	v_mfma_f32_16x16x32_bf16 v[34:37], v[190:193], v[228:231], v[34:37]
	s_barrier
	s_cbranch_scc0 .LBB0_405
	s_and_b64 vcc, exec, s[56:57]
	s_cbranch_vccz .LBB0_408
	s_barrier

.LBB0_584:
	s_add_u32 s47, s56, 0xfffc0080
	s_addc_u32 s58, s57, -1
	s_add_i32 s65, 0, 0x10000
	s_cmp_eq_u32 s45, 12
	s_cselect_b32 s61, s53, s58
	s_cselect_b32 s60, s52, s47
	s_cselect_b32 s59, s55, s19
	s_cselect_b32 s58, s54, s18
	s_add_i32 s47, 0, 0x14000
	v_add_u32_e32 v152, s65, v157
	v_add_u32_e32 v159, s47, v157
	ds_read_b128 v[130:133], v152
	ds_read_b128 v[144:147], v152 offset:1024
	ds_read_b128 v[148:151], v152 offset:2048
	ds_read_b128 v[152:155], v152 offset:3072
	ds_read_b128 v[176:179], v159
	ds_read_b128 v[180:183], v159 offset:1024
	ds_read_b128 v[184:187], v159 offset:2048
	ds_read_b128 v[188:191], v159 offset:3072
	s_add_i32 m0, s1, 0xc000
	ds_read_b128 v[192:195], v158
	ds_read_b128 v[196:199], v158 offset:1024
	ds_read_b128 v[200:203], v158 offset:2048
	ds_read_b128 v[204:207], v158 offset:3072
	ds_read_b128 v[208:211], v158 offset:4096
	ds_read_b128 v[212:215], v158 offset:5120
	ds_read_b128 v[224:227], v158 offset:6144
	ds_read_b128 v[228:231], v158 offset:7168
	global_load_lds_dwordx4 v140, s[56:57]
	s_add_i32 m0, s1, 0xe000
	s_nop 0
	global_load_lds_dwordx4 v142, s[56:57]
	s_waitcnt vmcnt(8)
	s_waitcnt lgkmcnt(0)
	s_barrier
	v_mfma_f32_16x16x32_bf16 v[126:129], v[130:133], v[192:195], v[126:129]
	v_mfma_f32_16x16x32_bf16 v[122:125], v[148:151], v[192:195], v[122:125]
	v_mfma_f32_16x16x32_bf16 v[118:121], v[130:133], v[200:203], v[118:121]
	v_mfma_f32_16x16x32_bf16 v[110:113], v[148:151], v[200:203], v[110:113]
	v_mfma_f32_16x16x32_bf16 v[102:105], v[130:133], v[208:211], v[102:105]
	v_mfma_f32_16x16x32_bf16 v[94:97], v[148:151], v[208:211], v[94:97]
	v_mfma_f32_16x16x32_bf16 v[86:89], v[130:133], v[224:227], v[86:89]
	v_mfma_f32_16x16x32_bf16 v[78:81], v[148:151], v[224:227], v[78:81]
	v_mfma_f32_16x16x32_bf16 v[126:129], v[144:147], v[196:199], v[126:129]
	v_mfma_f32_16x16x32_bf16 v[122:125], v[152:155], v[196:199], v[122:125]
	v_mfma_f32_16x16x32_bf16 v[118:121], v[144:147], v[204:207], v[118:121]
	v_mfma_f32_16x16x32_bf16 v[110:113], v[152:155], v[204:207], v[110:113]
	v_mfma_f32_16x16x32_bf16 v[102:105], v[144:147], v[212:215], v[102:105]
	v_mfma_f32_16x16x32_bf16 v[94:97], v[152:155], v[212:215], v[94:97]
	v_mfma_f32_16x16x32_bf16 v[86:89], v[144:147], v[228:231], v[86:89]
	v_mfma_f32_16x16x32_bf16 v[78:81], v[152:155], v[228:231], v[78:81]
	v_mfma_f32_16x16x32_bf16 v[114:117], v[176:179], v[192:195], v[114:117]
	v_mfma_f32_16x16x32_bf16 v[106:109], v[184:187], v[192:195], v[106:109]
	v_mfma_f32_16x16x32_bf16 v[98:101], v[176:179], v[200:203], v[98:101]
	v_mfma_f32_16x16x32_bf16 v[90:93], v[184:187], v[200:203], v[90:93]
	v_mfma_f32_16x16x32_bf16 v[82:85], v[176:179], v[208:211], v[82:85]
	v_mfma_f32_16x16x32_bf16 v[74:77], v[184:187], v[208:211], v[74:77]
	v_mfma_f32_16x16x32_bf16 v[70:73], v[176:179], v[224:227], v[70:73]
	v_mfma_f32_16x16x32_bf16 v[66:69], v[184:187], v[224:227], v[66:69]
	v_mfma_f32_16x16x32_bf16 v[114:117], v[180:183], v[196:199], v[114:117]
	v_mfma_f32_16x16x32_bf16 v[106:109], v[188:191], v[196:199], v[106:109]
	v_mfma_f32_16x16x32_bf16 v[98:101], v[180:183], v[204:207], v[98:101]
	v_mfma_f32_16x16x32_bf16 v[90:93], v[188:191], v[204:207], v[90:93]
	v_mfma_f32_16x16x32_bf16 v[82:85], v[180:183], v[212:215], v[82:85]
	v_mfma_f32_16x16x32_bf16 v[74:77], v[188:191], v[212:215], v[74:77]
	v_mfma_f32_16x16x32_bf16 v[70:73], v[180:183], v[228:231], v[70:73]
	v_mfma_f32_16x16x32_bf16 v[66:69], v[188:191], v[228:231], v[66:69]
	s_barrier
	s_add_u32 s98, s58, s28
	s_addc_u32 s99, s59, s29
	s_add_u32 s100, s60, s28
	s_addc_u32 s101, s61, s29
	s_add_i32 s65, s65, s0
	s_mov_b32 m0, s65
	ds_read_b128 v[192:195], v158 offset:16384
	ds_read_b128 v[196:199], v158 offset:17408
	ds_read_b128 v[200:203], v158 offset:18432
	ds_read_b128 v[204:207], v158 offset:19456
	ds_read_b128 v[208:211], v158 offset:20480
	ds_read_b128 v[212:215], v158 offset:21504
	ds_read_b128 v[224:227], v158 offset:22528
	ds_read_b128 v[228:231], v158 offset:23552
	global_load_lds_dwordx4 v32, s[58:59]
	s_add_i32 m0, s65, 0x2000
	s_add_u32 s66, s58, 0x40000
	s_addc_u32 s67, s59, 0
	s_add_i32 s47, s47, s0
	global_load_lds_dwordx4 v134, s[58:59]
	s_mov_b32 m0, s47
	s_nop 0
	global_load_lds_dwordx4 v32, s[66:67]
	s_add_i32 m0, s47, 0x2000
	s_nop 0
	global_load_lds_dwordx4 v134, s[66:67]
	s_mov_b32 m0, s1
	s_nop 0
	global_load_lds_dwordx4 v138, s[60:61]
	s_mov_b32 m0, s4
	s_nop 0
	global_load_lds_dwordx4 v136, s[60:61]
	s_waitcnt vmcnt(8)
	s_waitcnt lgkmcnt(0)
	s_barrier
	v_mfma_f32_16x16x32_bf16 v[62:65], v[130:133], v[192:195], v[62:65]
	v_mfma_f32_16x16x32_bf16 v[58:61], v[148:151], v[192:195], v[58:61]
	v_mfma_f32_16x16x32_bf16 v[54:57], v[130:133], v[200:203], v[54:57]
	v_mfma_f32_16x16x32_bf16 v[46:49], v[148:151], v[200:203], v[46:49]
	v_mfma_f32_16x16x32_bf16 v[38:41], v[130:133], v[208:211], v[38:41]
	v_mfma_f32_16x16x32_bf16 v[28:31], v[148:151], v[208:211], v[28:31]
	v_mfma_f32_16x16x32_bf16 v[20:23], v[130:133], v[224:227], v[20:23]
	v_mfma_f32_16x16x32_bf16 v[12:15], v[148:151], v[224:227], v[12:15]
	v_mfma_f32_16x16x32_bf16 v[62:65], v[144:147], v[196:199], v[62:65]
	v_mfma_f32_16x16x32_bf16 v[58:61], v[152:155], v[196:199], v[58:61]
	v_mfma_f32_16x16x32_bf16 v[54:57], v[144:147], v[204:207], v[54:57]
	v_mfma_f32_16x16x32_bf16 v[46:49], v[152:155], v[204:207], v[46:49]
	v_mfma_f32_16x16x32_bf16 v[38:41], v[144:147], v[212:215], v[38:41]
	v_mfma_f32_16x16x32_bf16 v[28:31], v[152:155], v[212:215], v[28:31]
	v_mfma_f32_16x16x32_bf16 v[20:23], v[144:147], v[228:231], v[20:23]
	v_mfma_f32_16x16x32_bf16 v[12:15], v[152:155], v[228:231], v[12:15]
	v_mfma_f32_16x16x32_bf16 v[50:53], v[176:179], v[192:195], v[50:53]
	v_mfma_f32_16x16x32_bf16 v[42:45], v[184:187], v[192:195], v[42:45]
	v_mfma_f32_16x16x32_bf16 v[34:37], v[176:179], v[200:203], v[34:37]
	v_mfma_f32_16x16x32_bf16 v[24:27], v[184:187], v[200:203], v[24:27]
	v_mfma_f32_16x16x32_bf16 v[16:19], v[176:179], v[208:211], v[16:19]
	v_mfma_f32_16x16x32_bf16 v[8:11], v[184:187], v[208:211], v[8:11]
	v_mfma_f32_16x16x32_bf16 v[4:7], v[176:179], v[224:227], v[4:7]
	v_mfma_f32_16x16x32_bf16 v[0:3], v[184:187], v[224:227], v[0:3]
	v_mfma_f32_16x16x32_bf16 v[50:53], v[180:183], v[196:199], v[50:53]
	v_mfma_f32_16x16x32_bf16 v[42:45], v[188:191], v[196:199], v[42:45]
	v_mfma_f32_16x16x32_bf16 v[34:37], v[180:183], v[204:207], v[34:37]
	v_mfma_f32_16x16x32_bf16 v[24:27], v[188:191], v[204:207], v[24:27]
	v_mfma_f32_16x16x32_bf16 v[16:19], v[180:183], v[212:215], v[16:19]
	v_mfma_f32_16x16x32_bf16 v[8:11], v[188:191], v[212:215], v[8:11]
	v_mfma_f32_16x16x32_bf16 v[4:7], v[180:183], v[228:231], v[4:7]
	v_mfma_f32_16x16x32_bf16 v[0:3], v[188:191], v[228:231], v[0:3]
	s_barrier
	s_add_i32 s47, 0, 0x18000
	s_add_i32 s65, 0, 0x1c000
	v_add_u32_e32 v152, s47, v157
	v_add_u32_e32 v159, s65, v157
	ds_read_b128 v[130:133], v152
	ds_read_b128 v[144:147], v152 offset:1024
	ds_read_b128 v[148:151], v152 offset:2048
	ds_read_b128 v[152:155], v152 offset:3072
	ds_read_b128 v[176:179], v159
	ds_read_b128 v[180:183], v159 offset:1024
	ds_read_b128 v[184:187], v159 offset:2048
	ds_read_b128 v[188:191], v159 offset:3072
	s_add_u32 s60, s60, 0x40000
	s_addc_u32 s61, s61, 0
	s_mov_b32 m0, s5
	ds_read_b128 v[192:195], v158 offset:32768
	ds_read_b128 v[196:199], v158 offset:33792
	ds_read_b128 v[200:203], v158 offset:34816
	ds_read_b128 v[204:207], v158 offset:35840
	ds_read_b128 v[208:211], v158 offset:36864
	ds_read_b128 v[212:215], v158 offset:37888
	ds_read_b128 v[224:227], v158 offset:38912
	ds_read_b128 v[228:231], v158 offset:39936
	global_load_lds_dwordx4 v138, s[60:61]
	s_mov_b32 m0, s8
	s_nop 0
	global_load_lds_dwordx4 v136, s[60:61]
	s_waitcnt vmcnt(8)
	s_waitcnt lgkmcnt(0)
	s_barrier
	v_mfma_f32_16x16x32_bf16 v[126:129], v[130:133], v[192:195], v[126:129]
	v_mfma_f32_16x16x32_bf16 v[122:125], v[148:151], v[192:195], v[122:125]
	v_mfma_f32_16x16x32_bf16 v[118:121], v[130:133], v[200:203], v[118:121]
	v_mfma_f32_16x16x32_bf16 v[110:113], v[148:151], v[200:203], v[110:113]
	v_mfma_f32_16x16x32_bf16 v[102:105], v[130:133], v[208:211], v[102:105]
	v_mfma_f32_16x16x32_bf16 v[94:97], v[148:151], v[208:211], v[94:97]
	v_mfma_f32_16x16x32_bf16 v[86:89], v[130:133], v[224:227], v[86:89]
	v_mfma_f32_16x16x32_bf16 v[78:81], v[148:151], v[224:227], v[78:81]
	v_mfma_f32_16x16x32_bf16 v[126:129], v[144:147], v[196:199], v[126:129]
	v_mfma_f32_16x16x32_bf16 v[122:125], v[152:155], v[196:199], v[122:125]
	v_mfma_f32_16x16x32_bf16 v[118:121], v[144:147], v[204:207], v[118:121]
	v_mfma_f32_16x16x32_bf16 v[110:113], v[152:155], v[204:207], v[110:113]
	v_mfma_f32_16x16x32_bf16 v[102:105], v[144:147], v[212:215], v[102:105]
	v_mfma_f32_16x16x32_bf16 v[94:97], v[152:155], v[212:215], v[94:97]
	v_mfma_f32_16x16x32_bf16 v[86:89], v[144:147], v[228:231], v[86:89]
	v_mfma_f32_16x16x32_bf16 v[78:81], v[152:155], v[228:231], v[78:81]
	v_mfma_f32_16x16x32_bf16 v[114:117], v[176:179], v[192:195], v[114:117]
	v_mfma_f32_16x16x32_bf16 v[106:109], v[184:187], v[192:195], v[106:109]
	v_mfma_f32_16x16x32_bf16 v[98:101], v[176:179], v[200:203], v[98:101]
	v_mfma_f32_16x16x32_bf16 v[90:93], v[184:187], v[200:203], v[90:93]
	v_mfma_f32_16x16x32_bf16 v[82:85], v[176:179], v[208:211], v[82:85]
	v_mfma_f32_16x16x32_bf16 v[74:77], v[184:187], v[208:211], v[74:77]
	v_mfma_f32_16x16x32_bf16 v[70:73], v[176:179], v[224:227], v[70:73]
	v_mfma_f32_16x16x32_bf16 v[66:69], v[184:187], v[224:227], v[66:69]
	v_mfma_f32_16x16x32_bf16 v[114:117], v[180:183], v[196:199], v[114:117]
	v_mfma_f32_16x16x32_bf16 v[106:109], v[188:191], v[196:199], v[106:109]
	v_mfma_f32_16x16x32_bf16 v[98:101], v[180:183], v[204:207], v[98:101]
	v_mfma_f32_16x16x32_bf16 v[90:93], v[188:191], v[204:207], v[90:93]
	v_mfma_f32_16x16x32_bf16 v[82:85], v[180:183], v[212:215], v[82:85]
	v_mfma_f32_16x16x32_bf16 v[74:77], v[188:191], v[212:215], v[74:77]
	v_mfma_f32_16x16x32_bf16 v[70:73], v[180:183], v[228:231], v[70:73]
	v_mfma_f32_16x16x32_bf16 v[66:69], v[188:191], v[228:231], v[66:69]
	s_barrier
	s_add_i32 s47, s47, s0
	s_mov_b32 m0, s47
	ds_read_b128 v[192:195], v158 offset:49152
	ds_read_b128 v[196:199], v158 offset:50176
	ds_read_b128 v[200:203], v158 offset:51200
	ds_read_b128 v[204:207], v158 offset:52224
	ds_read_b128 v[208:211], v158 offset:53248
	ds_read_b128 v[212:215], v158 offset:54272
	ds_read_b128 v[224:227], v158 offset:55296
	ds_read_b128 v[228:231], v158 offset:56320
	global_load_lds_dwordx4 v32, s[98:99]
	s_add_i32 m0, s47, 0x2000
	s_add_u32 s58, s58, 0x40080
	s_addc_u32 s59, s59, 0
	s_add_i32 s47, s65, s0
	global_load_lds_dwordx4 v134, s[98:99]
	s_mov_b32 m0, s47
	s_nop 0
	global_load_lds_dwordx4 v32, s[58:59]
	s_add_i32 m0, s47, 0x2000
	s_nop 0
	global_load_lds_dwordx4 v134, s[58:59]
	s_mov_b32 m0, s33
	s_nop 0
	global_load_lds_dwordx4 v138, s[100:101]
	s_mov_b32 m0, s38
	s_nop 0
	global_load_lds_dwordx4 v136, s[100:101]
	s_waitcnt vmcnt(8)
	s_waitcnt lgkmcnt(0)
	s_barrier
	v_mfma_f32_16x16x32_bf16 v[62:65], v[130:133], v[192:195], v[62:65]
	v_mfma_f32_16x16x32_bf16 v[58:61], v[148:151], v[192:195], v[58:61]
	s_add_i32 s45, s45, 2
	s_add_u32 s56, s56, 0x100
	s_addc_u32 s57, s57, 0
	s_add_u32 s18, s18, 0x100
	s_addc_u32 s19, s19, 0
	s_cmp_gt_u32 s45, 13
	v_mfma_f32_16x16x32_bf16 v[54:57], v[130:133], v[200:203], v[54:57]
	v_mfma_f32_16x16x32_bf16 v[46:49], v[148:151], v[200:203], v[46:49]
	v_mfma_f32_16x16x32_bf16 v[38:41], v[130:133], v[208:211], v[38:41]
	v_mfma_f32_16x16x32_bf16 v[28:31], v[148:151], v[208:211], v[28:31]
	v_mfma_f32_16x16x32_bf16 v[20:23], v[130:133], v[224:227], v[20:23]
	v_mfma_f32_16x16x32_bf16 v[12:15], v[148:151], v[224:227], v[12:15]
	v_mfma_f32_16x16x32_bf16 v[62:65], v[144:147], v[196:199], v[62:65]
	v_mfma_f32_16x16x32_bf16 v[58:61], v[152:155], v[196:199], v[58:61]
	v_mfma_f32_16x16x32_bf16 v[54:57], v[144:147], v[204:207], v[54:57]
	v_mfma_f32_16x16x32_bf16 v[46:49], v[152:155], v[204:207], v[46:49]
	v_mfma_f32_16x16x32_bf16 v[38:41], v[144:147], v[212:215], v[38:41]
	v_mfma_f32_16x16x32_bf16 v[28:31], v[152:155], v[212:215], v[28:31]
	v_mfma_f32_16x16x32_bf16 v[20:23], v[144:147], v[228:231], v[20:23]
	v_mfma_f32_16x16x32_bf16 v[12:15], v[152:155], v[228:231], v[12:15]
	v_mfma_f32_16x16x32_bf16 v[50:53], v[176:179], v[192:195], v[50:53]
	v_mfma_f32_16x16x32_bf16 v[42:45], v[184:187], v[192:195], v[42:45]
	v_mfma_f32_16x16x32_bf16 v[34:37], v[176:179], v[200:203], v[34:37]
	v_mfma_f32_16x16x32_bf16 v[24:27], v[184:187], v[200:203], v[24:27]
	v_mfma_f32_16x16x32_bf16 v[16:19], v[176:179], v[208:211], v[16:19]
	v_mfma_f32_16x16x32_bf16 v[8:11], v[184:187], v[208:211], v[8:11]
	v_mfma_f32_16x16x32_bf16 v[4:7], v[176:179], v[224:227], v[4:7]
	v_mfma_f32_16x16x32_bf16 v[0:3], v[184:187], v[224:227], v[0:3]
	v_mfma_f32_16x16x32_bf16 v[50:53], v[180:183], v[196:199], v[50:53]
	v_mfma_f32_16x16x32_bf16 v[42:45], v[188:191], v[196:199], v[42:45]
	v_mfma_f32_16x16x32_bf16 v[34:37], v[180:183], v[204:207], v[34:37]
	v_mfma_f32_16x16x32_bf16 v[24:27], v[188:191], v[204:207], v[24:27]
	v_mfma_f32_16x16x32_bf16 v[16:19], v[180:183], v[212:215], v[16:19]
	v_mfma_f32_16x16x32_bf16 v[8:11], v[188:191], v[212:215], v[8:11]
	v_mfma_f32_16x16x32_bf16 v[4:7], v[180:183], v[228:231], v[4:7]
	v_mfma_f32_16x16x32_bf16 v[0:3], v[188:191], v[228:231], v[0:3]
	s_barrier
	s_cbranch_scc0 .LBB0_584
	s_and_b64 vcc, exec, s[24:25]
	s_cbranch_vccz .LBB0_587
	s_barrier
